# LRU: refined sqrtf sequences replaced by v_sqrt_f32 (32 sites); F phase: hy_out_tr items moved to the half of the grid that has no HGRN items
# speedup vs baseline: 1.0704x; 1.0038x over previous
; __device__ __forceinline__ bf16_t f2bf(float f) { return (bf16_t)(cvt_pk_bf16(f, 0.f) & 0xffffu); }
; __device__ __forceinline__ float bf2f(bf16_t b) { return __uint_as_float(((unsigned)b) << 16); }
; __device__ __forceinline__ float sigmoidf_(float x) { return 1.0f / (1.0f + __expf(-x)); }
; template <bool FINAL>
; __device__ __forceinline__ void lru_item(const Ctx& C, int l, int item) {
;     ...
; #pragma unroll 1
;         for (int s4 = 0; s4 < 4; ++s4) { const int tt = z ? 3 - s4 : s4;
;             const bf16_t* xrow = xc + (16 * tt + fr) * XCP + n * 64 + 8 * quad;
;             const bf16x8 xa0 = *(const bf16x8*)xrow, xa1 = *(const bf16x8*)(xrow + 32);
; #pragma unroll
;             for (int dt = 0; dt < 4; ++dt) {
;                 f32x4 Da = {0.f, 0.f, 0.f, 0.f}, Dx = {0.f, 0.f, 0.f, 0.f};
;                 Da = __builtin_amdgcn_mfma_f32_16x16x32_bf16(xa0, Bw[0][dt][0], Da, 0, 0, 0); Da = __builtin_amdgcn_mfma_f32_16x16x32_bf16(xa1, Bw[0][dt][1], Da, 0, 0, 0);
;                 Dx = __builtin_amdgcn_mfma_f32_16x16x32_bf16(xa0, Bw[1][dt][0], Dx, 0, 0, 0); Dx = __builtin_amdgcn_mfma_f32_16x16x32_bf16(xa1, Bw[1][dt][1], Dx, 0, 0, 0);
; #pragma unroll
;                 for (int r = 0; r < 4; ++r) { const int tloc = 4 * quad + r, d = 16 * dt + fr;
;                     const float rg = sigmoidf_(Da[r] + bav[dt]), ig = sigmoidf_(Dx[r] + bxv[dt]), la = -8.0f * rg * spv[dt], a = __expf(la);
;                     const float x = bf2f(xc[(16 * tt + tloc) * XCP + n * 64 + d]);
;                     Al[tloc * 68 + d] = a; Ul[tloc * 68 + d] = f2bf(sqrtf(fmaxf(1.0f - a * a, 0.f)) * ig * x); }
.LBB0_466:
	s_and_b64 s[0:1], s[4:5], exec
	s_cselect_b32 s0, s19, s20
	s_lshl_b32 s21, s0, 4
	v_or_b32_e32 v66, s21, v93
	v_mad_u64_u32 v[66:67], s[0:1], v66, s58, v[92:93]
	ds_read_b128 v[70:73], v66
	ds_read_b128 v[66:69], v66 offset:64
	s_add_i32 s19, s19, 1
	s_add_i32 s20, s20, -1
	s_waitcnt lgkmcnt(1)
	v_mfma_f32_16x16x32_bf16 v[74:77], v[70:73], v[0:3], 0
	s_cmp_lg_u32 s19, 4
	s_waitcnt lgkmcnt(0)
	v_mfma_f32_16x16x32_bf16 v[74:77], v[66:69], v[16:19], v[74:77]
	v_mfma_f32_16x16x32_bf16 v[98:101], v[70:73], v[32:35], 0
	v_mfma_f32_16x16x32_bf16 v[168:171], v[66:69], v[48:51], v[98:101]
	s_nop 5
	v_add_f32_e32 v74, v64, v74
	v_mul_f32_e32 v74, 0xbfb8aa3b, v74
	v_exp_f32_e32 v74, v74
	s_nop 0
	v_add_f32_e32 v74, 1.0, v74
	s_nop 0
	v_rcp_f32_e32 v74, v74
	v_add_f32_e32 v98, v155, v168
	v_mul_f32_e32 v98, 0xbfb8aa3b, v98
	v_exp_f32_e32 v98, v98
	v_mul_f32_e32 v74, 0xc1000000, v74
	v_mul_f32_e32 v74, v156, v74
	v_mul_f32_e32 v74, 0x3fb8aa3b, v74
	v_add_f32_e32 v98, 1.0, v98
	v_exp_f32_e32 v74, v74
	ds_write_b32 v108, v74 offset:33792
	v_fma_f32 v74, -v74, v74, 1.0
	v_max_f32_e32 v74, 0, v74
	v_rcp_f32_e32 v98, v98
	v_or_b32_e32 v99, s21, v106
	v_mad_u64_u32 v[104:105], s[0:1], v99, s58, v[96:97]
	ds_read_u16 v99, v104
	s_waitcnt lgkmcnt(0)
	v_lshlrev_b32_e32 v99, 16, v99
	s_nop 1
	v_sqrt_f32_e32 v74, v74
	s_nop 0
	v_mul_f32_e32 v74, v98, v74
	v_mul_f32_e32 v74, v74, v99
	v_cvt_pk_bf16_f32 v74, v74, s0
	ds_write_b16 v136, v74 offset:38144
	v_add_f32_e32 v74, v64, v75
	v_mul_f32_e32 v74, 0xbfb8aa3b, v74
	v_exp_f32_e32 v74, v74
	s_nop 0
	v_add_f32_e32 v74, 1.0, v74
	s_nop 0
	v_rcp_f32_e32 v74, v74
	v_add_f32_e32 v75, v155, v169
	v_mul_f32_e32 v75, 0xbfb8aa3b, v75
	v_exp_f32_e32 v75, v75
	v_mul_f32_e32 v74, 0xc1000000, v74
	v_mul_f32_e32 v74, v156, v74
	v_mul_f32_e32 v74, 0x3fb8aa3b, v74
	v_add_f32_e32 v75, 1.0, v75
	v_exp_f32_e32 v74, v74
	ds_write_b32 v110, v74 offset:33792
	v_fma_f32 v74, -v74, v74, 1.0
	v_max_f32_e32 v74, 0, v74
	v_rcp_f32_e32 v75, v75
	v_or_b32_e32 v98, s21, v109
	v_mad_u64_u32 v[102:103], s[0:1], v98, s58, v[96:97]
	ds_read_u16 v98, v102
	s_waitcnt lgkmcnt(0)
	v_lshlrev_b32_e32 v98, 16, v98
	s_nop 1
	v_sqrt_f32_e32 v74, v74
	s_nop 0
	v_mul_f32_e32 v74, v75, v74
	v_mul_f32_e32 v74, v74, v98
	v_cvt_pk_bf16_f32 v74, v74, s0
	ds_write_b16 v137, v74 offset:38144
	v_add_f32_e32 v74, v64, v76
	v_mul_f32_e32 v74, 0xbfb8aa3b, v74
	v_exp_f32_e32 v74, v74
	s_nop 0
	v_add_f32_e32 v74, 1.0, v74
	s_nop 0
	v_rcp_f32_e32 v74, v74
	v_add_f32_e32 v75, v155, v170
	v_mul_f32_e32 v75, 0xbfb8aa3b, v75
	v_exp_f32_e32 v75, v75
	v_mul_f32_e32 v74, 0xc1000000, v74
	v_mul_f32_e32 v74, v156, v74
	v_mul_f32_e32 v74, 0x3fb8aa3b, v74
	v_add_f32_e32 v75, 1.0, v75
	v_exp_f32_e32 v74, v74
	ds_write_b32 v112, v74 offset:33792
	v_fma_f32 v74, -v74, v74, 1.0
	v_max_f32_e32 v74, 0, v74
	v_rcp_f32_e32 v75, v75
	v_or_b32_e32 v76, s21, v111
	v_mad_u64_u32 v[100:101], s[0:1], v76, s58, v[96:97]
	ds_read_u16 v76, v100
	s_waitcnt lgkmcnt(0)
	v_lshlrev_b32_e32 v76, 16, v76
	s_nop 1
	v_sqrt_f32_e32 v74, v74
	s_nop 0
	v_mul_f32_e32 v74, v75, v74
	v_mul_f32_e32 v74, v74, v76
	v_cvt_pk_bf16_f32 v74, v74, s0
	ds_write_b16 v138, v74 offset:38144
	v_add_f32_e32 v74, v64, v77
	v_mul_f32_e32 v74, 0xbfb8aa3b, v74
	v_exp_f32_e32 v74, v74
	s_nop 0
	v_add_f32_e32 v74, 1.0, v74
	s_nop 0
	v_rcp_f32_e32 v74, v74
	v_add_f32_e32 v75, v155, v171
	v_mul_f32_e32 v75, 0xbfb8aa3b, v75
	v_exp_f32_e32 v75, v75
	v_mul_f32_e32 v74, 0xc1000000, v74
	v_mul_f32_e32 v74, v156, v74
	v_mul_f32_e32 v74, 0x3fb8aa3b, v74
	v_add_f32_e32 v75, 1.0, v75
	v_exp_f32_e32 v74, v74
	v_mfma_f32_16x16x32_bf16 v[168:171], v[70:73], v[36:39], 0
	ds_write_b32 v114, v74 offset:33792
	v_fma_f32 v74, -v74, v74, 1.0
	v_max_f32_e32 v74, 0, v74
	v_rcp_f32_e32 v75, v75
	v_or_b32_e32 v76, s21, v113
	v_mad_u64_u32 v[98:99], s[0:1], v76, s58, v[96:97]
	ds_read_u16 v76, v98
	v_mfma_f32_16x16x32_bf16 v[168:171], v[66:69], v[52:55], v[168:171]
	s_waitcnt lgkmcnt(0)
	v_lshlrev_b32_e32 v76, 16, v76
	s_nop 1
	v_sqrt_f32_e32 v74, v74
	s_nop 0
	v_mul_f32_e32 v74, v75, v74
	v_mul_f32_e32 v74, v74, v76
	v_cvt_pk_bf16_f32 v74, v74, s0
	ds_write_b16 v139, v74 offset:38144
	v_mfma_f32_16x16x32_bf16 v[74:77], v[70:73], v[4:7], 0
	v_mfma_f32_16x16x32_bf16 v[74:77], v[66:69], v[20:23], v[74:77]
	s_nop 7
	v_add_f32_e32 v74, v157, v74
	v_mul_f32_e32 v74, 0xbfb8aa3b, v74
	v_exp_f32_e32 v74, v74
	s_nop 0
	v_add_f32_e32 v74, 1.0, v74
	s_nop 0
	v_rcp_f32_e32 v74, v74
	v_add_f32_e32 v99, v158, v168
	v_mul_f32_e32 v99, 0xbfb8aa3b, v99
	v_exp_f32_e32 v99, v99
	v_mul_f32_e32 v74, 0xc1000000, v74
	v_mul_f32_e32 v74, v159, v74
	v_mul_f32_e32 v74, 0x3fb8aa3b, v74
	v_add_f32_e32 v99, 1.0, v99
	v_exp_f32_e32 v74, v74
	ds_write_b32 v108, v74 offset:33856
	v_fma_f32 v74, -v74, v74, 1.0
	v_max_f32_e32 v74, 0, v74
	v_rcp_f32_e32 v99, v99
	ds_read_u16 v101, v104 offset:32
	s_waitcnt lgkmcnt(0)
	v_lshlrev_b32_e32 v101, 16, v101
	s_nop 1
	s_nop 1
	v_sqrt_f32_e32 v74, v74
	s_nop 0
	v_mul_f32_e32 v74, v99, v74
	v_mul_f32_e32 v74, v74, v101
	v_cvt_pk_bf16_f32 v74, v74, s0
	ds_write_b16 v115, v74 offset:38176
	v_add_f32_e32 v74, v157, v75
	v_mul_f32_e32 v74, 0xbfb8aa3b, v74
	v_exp_f32_e32 v74, v74
	s_nop 0
	v_add_f32_e32 v74, 1.0, v74
	s_nop 0
	v_rcp_f32_e32 v74, v74
	v_add_f32_e32 v75, v158, v169
	v_mul_f32_e32 v75, 0xbfb8aa3b, v75
	v_exp_f32_e32 v75, v75
	v_mul_f32_e32 v74, 0xc1000000, v74
	v_mul_f32_e32 v74, v159, v74
	v_mul_f32_e32 v74, 0x3fb8aa3b, v74
	v_add_f32_e32 v75, 1.0, v75
	v_exp_f32_e32 v74, v74
	ds_write_b32 v110, v74 offset:33856
	v_fma_f32 v74, -v74, v74, 1.0
	v_max_f32_e32 v74, 0, v74
	v_rcp_f32_e32 v75, v75
	ds_read_u16 v99, v102 offset:32
	s_waitcnt lgkmcnt(0)
; __device__ __forceinline__ bf16_t f2bf(float f) { return (bf16_t)(cvt_pk_bf16(f, 0.f) & 0xffffu); }
; __device__ __forceinline__ float bf2f(bf16_t b) { return __uint_as_float(((unsigned)b) << 16); }
; __device__ __forceinline__ float sigmoidf_(float x) { return 1.0f / (1.0f + __expf(-x)); }
; template <bool FINAL>
; __device__ __forceinline__ void lru_item(const Ctx& C, int l, int item) {
;     ...
;             for (int dt = 0; dt < 4; ++dt) {
;                 f32x4 Da = {0.f, 0.f, 0.f, 0.f}, Dx = {0.f, 0.f, 0.f, 0.f};
;                 Da = __builtin_amdgcn_mfma_f32_16x16x32_bf16(xa0, Bw[0][dt][0], Da, 0, 0, 0); Da = __builtin_amdgcn_mfma_f32_16x16x32_bf16(xa1, Bw[0][dt][1], Da, 0, 0, 0);
;                 Dx = __builtin_amdgcn_mfma_f32_16x16x32_bf16(xa0, Bw[1][dt][0], Dx, 0, 0, 0); Dx = __builtin_amdgcn_mfma_f32_16x16x32_bf16(xa1, Bw[1][dt][1], Dx, 0, 0, 0);
; #pragma unroll
;                 for (int r = 0; r < 4; ++r) { const int tloc = 4 * quad + r, d = 16 * dt + fr;
;                     const float rg = sigmoidf_(Da[r] + bav[dt]), ig = sigmoidf_(Dx[r] + bxv[dt]), la = -8.0f * rg * spv[dt], a = __expf(la);
;                     const float x = bf2f(xc[(16 * tt + tloc) * XCP + n * 64 + d]);
;                     Al[tloc * 68 + d] = a; Ul[tloc * 68 + d] = f2bf(sqrtf(fmaxf(1.0f - a * a, 0.f)) * ig * x); }
	v_lshlrev_b32_e32 v99, 16, v99
	s_nop 1
	s_nop 1
	v_sqrt_f32_e32 v74, v74
	s_nop 0
	v_mul_f32_e32 v74, v75, v74
	v_mul_f32_e32 v74, v74, v99
	v_cvt_pk_bf16_f32 v74, v74, s0
	ds_write_b16 v116, v74 offset:38176
	v_add_f32_e32 v74, v157, v76
	v_mul_f32_e32 v74, 0xbfb8aa3b, v74
	v_exp_f32_e32 v74, v74
	s_nop 0
	v_add_f32_e32 v74, 1.0, v74
	s_nop 0
	v_rcp_f32_e32 v74, v74
	v_add_f32_e32 v75, v158, v170
	v_mul_f32_e32 v75, 0xbfb8aa3b, v75
	v_exp_f32_e32 v75, v75
	v_mul_f32_e32 v74, 0xc1000000, v74
	v_mul_f32_e32 v74, v159, v74
	v_mul_f32_e32 v74, 0x3fb8aa3b, v74
	v_add_f32_e32 v75, 1.0, v75
	v_exp_f32_e32 v74, v74
	ds_write_b32 v112, v74 offset:33856
	v_fma_f32 v74, -v74, v74, 1.0
	v_max_f32_e32 v74, 0, v74
	v_rcp_f32_e32 v75, v75
	ds_read_u16 v76, v100 offset:32
	s_waitcnt lgkmcnt(0)
	v_lshlrev_b32_e32 v76, 16, v76
	s_nop 1
	s_nop 1
	v_sqrt_f32_e32 v74, v74
	s_nop 0
	v_mul_f32_e32 v74, v75, v74
	v_mul_f32_e32 v74, v74, v76
	v_cvt_pk_bf16_f32 v74, v74, s0
	ds_write_b16 v117, v74 offset:38176
	v_add_f32_e32 v74, v157, v77
	v_mul_f32_e32 v74, 0xbfb8aa3b, v74
	v_exp_f32_e32 v74, v74
	s_nop 0
	v_add_f32_e32 v74, 1.0, v74
	s_nop 0
	v_rcp_f32_e32 v74, v74
	v_add_f32_e32 v75, v158, v171
	v_mul_f32_e32 v75, 0xbfb8aa3b, v75
	v_exp_f32_e32 v75, v75
	v_mul_f32_e32 v74, 0xc1000000, v74
	v_mul_f32_e32 v74, v159, v74
	v_mul_f32_e32 v74, 0x3fb8aa3b, v74
	v_add_f32_e32 v75, 1.0, v75
	v_exp_f32_e32 v74, v74
	v_mfma_f32_16x16x32_bf16 v[168:171], v[70:73], v[40:43], 0
	ds_write_b32 v114, v74 offset:33856
	v_fma_f32 v74, -v74, v74, 1.0
	v_max_f32_e32 v74, 0, v74
	v_rcp_f32_e32 v75, v75
	ds_read_u16 v76, v98 offset:32
	v_mfma_f32_16x16x32_bf16 v[168:171], v[66:69], v[56:59], v[168:171]
	s_waitcnt lgkmcnt(0)
	v_lshlrev_b32_e32 v76, 16, v76
	s_nop 1
	s_nop 1
	v_sqrt_f32_e32 v74, v74
	s_nop 0
	v_mul_f32_e32 v74, v75, v74
	v_mul_f32_e32 v74, v74, v76
	v_cvt_pk_bf16_f32 v74, v74, s0
	ds_write_b16 v118, v74 offset:38176
	v_mfma_f32_16x16x32_bf16 v[74:77], v[70:73], v[8:11], 0
	v_mfma_f32_16x16x32_bf16 v[74:77], v[66:69], v[24:27], v[74:77]
	s_nop 7
	v_add_f32_e32 v74, v160, v74
	v_mul_f32_e32 v74, 0xbfb8aa3b, v74
	v_exp_f32_e32 v74, v74
	s_nop 0
	v_add_f32_e32 v74, 1.0, v74
	s_nop 0
	v_rcp_f32_e32 v74, v74
	v_add_f32_e32 v99, v161, v168
	v_mul_f32_e32 v99, 0xbfb8aa3b, v99
	v_exp_f32_e32 v99, v99
	v_mul_f32_e32 v74, 0xc1000000, v74
	v_mul_f32_e32 v74, v162, v74
	v_mul_f32_e32 v74, 0x3fb8aa3b, v74
	v_add_f32_e32 v99, 1.0, v99
	v_exp_f32_e32 v74, v74
	ds_write_b32 v108, v74 offset:33920
	v_fma_f32 v74, -v74, v74, 1.0
	v_max_f32_e32 v74, 0, v74
	v_rcp_f32_e32 v99, v99
	ds_read_u16 v101, v104 offset:64
	s_waitcnt lgkmcnt(0)
	v_lshlrev_b32_e32 v101, 16, v101
	s_nop 1
	s_nop 1
	v_sqrt_f32_e32 v74, v74
	s_nop 0
	v_mul_f32_e32 v74, v99, v74
	v_mul_f32_e32 v74, v74, v101
	v_cvt_pk_bf16_f32 v74, v74, s0
	ds_write_b16 v115, v74 offset:38208
	v_add_f32_e32 v74, v160, v75
	v_mul_f32_e32 v74, 0xbfb8aa3b, v74
	v_exp_f32_e32 v74, v74
	s_nop 0
	v_add_f32_e32 v74, 1.0, v74
	s_nop 0
	v_rcp_f32_e32 v74, v74
	v_add_f32_e32 v75, v161, v169
	v_mul_f32_e32 v75, 0xbfb8aa3b, v75
	v_exp_f32_e32 v75, v75
	v_mul_f32_e32 v74, 0xc1000000, v74
	v_mul_f32_e32 v74, v162, v74
	v_mul_f32_e32 v74, 0x3fb8aa3b, v74
	v_add_f32_e32 v75, 1.0, v75
	v_exp_f32_e32 v74, v74
	ds_write_b32 v110, v74 offset:33920
	v_fma_f32 v74, -v74, v74, 1.0
	v_max_f32_e32 v74, 0, v74
	v_rcp_f32_e32 v75, v75
	ds_read_u16 v99, v102 offset:64
	s_waitcnt lgkmcnt(0)
	v_lshlrev_b32_e32 v99, 16, v99
	s_nop 1
	s_nop 1
	v_sqrt_f32_e32 v74, v74
	s_nop 0
	v_mul_f32_e32 v74, v75, v74
	v_mul_f32_e32 v74, v74, v99
	v_cvt_pk_bf16_f32 v74, v74, s0
	ds_write_b16 v116, v74 offset:38208
	v_add_f32_e32 v74, v160, v76
	v_mul_f32_e32 v74, 0xbfb8aa3b, v74
	v_exp_f32_e32 v74, v74
	s_nop 0
	v_add_f32_e32 v74, 1.0, v74
	s_nop 0
	v_rcp_f32_e32 v74, v74
	v_add_f32_e32 v75, v161, v170
	v_mul_f32_e32 v75, 0xbfb8aa3b, v75
	v_exp_f32_e32 v75, v75
	v_mul_f32_e32 v74, 0xc1000000, v74
	v_mul_f32_e32 v74, v162, v74
	v_mul_f32_e32 v74, 0x3fb8aa3b, v74
	v_add_f32_e32 v75, 1.0, v75
	v_exp_f32_e32 v74, v74
	ds_write_b32 v112, v74 offset:33920
	v_fma_f32 v74, -v74, v74, 1.0
	v_max_f32_e32 v74, 0, v74
	v_rcp_f32_e32 v75, v75
	ds_read_u16 v76, v100 offset:64
	s_waitcnt lgkmcnt(0)
	v_lshlrev_b32_e32 v76, 16, v76
	s_nop 1
	s_nop 1
	v_sqrt_f32_e32 v74, v74
	s_nop 0
	v_mul_f32_e32 v74, v75, v74
	v_mul_f32_e32 v74, v74, v76
	v_cvt_pk_bf16_f32 v74, v74, s0
	ds_write_b16 v117, v74 offset:38208
	v_add_f32_e32 v74, v160, v77
	v_mul_f32_e32 v74, 0xbfb8aa3b, v74
	v_exp_f32_e32 v74, v74
	s_nop 0
	v_add_f32_e32 v74, 1.0, v74
	s_nop 0
	v_rcp_f32_e32 v74, v74
	v_add_f32_e32 v75, v161, v171
	v_mul_f32_e32 v75, 0xbfb8aa3b, v75
	v_exp_f32_e32 v75, v75
	v_mul_f32_e32 v74, 0xc1000000, v74
	v_mul_f32_e32 v74, v162, v74
	v_mul_f32_e32 v74, 0x3fb8aa3b, v74
	v_add_f32_e32 v75, 1.0, v75
	v_exp_f32_e32 v74, v74
	ds_write_b32 v114, v74 offset:33920
	v_fma_f32 v74, -v74, v74, 1.0
	v_max_f32_e32 v74, 0, v74
	v_rcp_f32_e32 v75, v75
	ds_read_u16 v76, v98 offset:64
	s_waitcnt lgkmcnt(0)
	v_lshlrev_b32_e32 v76, 16, v76
	s_nop 1
	s_nop 1
	v_sqrt_f32_e32 v74, v74
	s_nop 0
	v_mul_f32_e32 v74, v75, v74
	v_mul_f32_e32 v74, v74, v76
	v_cvt_pk_bf16_f32 v74, v74, s0
	ds_write_b16 v118, v74 offset:38208
	v_mfma_f32_16x16x32_bf16 v[74:77], v[70:73], v[12:15], 0
	v_mfma_f32_16x16x32_bf16 v[74:77], v[66:69], v[28:31], v[74:77]
	v_mfma_f32_16x16x32_bf16 v[70:73], v[70:73], v[44:47], 0
	v_mfma_f32_16x16x32_bf16 v[66:69], v[66:69], v[60:63], v[70:73]
	s_waitcnt vmcnt(1)
	s_nop 5
	v_add_f32_e32 v70, v163, v74
	v_mul_f32_e32 v70, 0xbfb8aa3b, v70
	v_exp_f32_e32 v70, v70
	s_waitcnt vmcnt(0)
; __device__ __forceinline__ bf16_t f2bf(float f) { return (bf16_t)(cvt_pk_bf16(f, 0.f) & 0xffffu); }
; __device__ __forceinline__ float bf2f(bf16_t b) { return __uint_as_float(((unsigned)b) << 16); }
; __device__ __forceinline__ float sigmoidf_(float x) { return 1.0f / (1.0f + __expf(-x)); }
; __device__ __forceinline__ void wave_lds_fence() { asm volatile("s_waitcnt lgkmcnt(0)" ::: "memory"); __builtin_amdgcn_wave_barrier(); }
;     __device__ __forceinline__ float* fp(size_t off) const { return (float*)(ws + off); }
; template <bool FINAL>
; __device__ __forceinline__ void lru_item(const Ctx& C, int l, int item) {
;     ...
;             for (int dt = 0; dt < 4; ++dt) {
;                 f32x4 Da = {0.f, 0.f, 0.f, 0.f}, Dx = {0.f, 0.f, 0.f, 0.f};
;                 Da = __builtin_amdgcn_mfma_f32_16x16x32_bf16(xa0, Bw[0][dt][0], Da, 0, 0, 0); Da = __builtin_amdgcn_mfma_f32_16x16x32_bf16(xa1, Bw[0][dt][1], Da, 0, 0, 0);
;                 Dx = __builtin_amdgcn_mfma_f32_16x16x32_bf16(xa0, Bw[1][dt][0], Dx, 0, 0, 0); Dx = __builtin_amdgcn_mfma_f32_16x16x32_bf16(xa1, Bw[1][dt][1], Dx, 0, 0, 0);
; #pragma unroll
;                 for (int r = 0; r < 4; ++r) { const int tloc = 4 * quad + r, d = 16 * dt + fr;
;                     const float rg = sigmoidf_(Da[r] + bav[dt]), ig = sigmoidf_(Dx[r] + bxv[dt]), la = -8.0f * rg * spv[dt], a = __expf(la);
;                     const float x = bf2f(xc[(16 * tt + tloc) * XCP + n * 64 + d]);
;                     Al[tloc * 68 + d] = a; Ul[tloc * 68 + d] = f2bf(sqrtf(fmaxf(1.0f - a * a, 0.f)) * ig * x); }
;             }
;             wave_lds_fence();
; #pragma unroll
;             for (int j = 0; j < 16; ++j) { const int tloc = z ? 15 - j : j;
;                 const float a = Al[tloc * 68 + lane], u = bf2f(Ul[tloc * 68 + lane]);
;                 h = fmaf(a, h, u); Ap *= a;
;                 if (FINAL) Hz[(16 * tt + tloc) * 256 + n * 64 + lane] = f2bf(h); }
;             wave_lds_fence();
;         }
;         if (!FINAL) { C.fp(OFF_CARA)[cidx] = Ap; C.fp(OFF_CARH)[cidx] = h; }
	v_add_f32_e32 v66, v164, v66
	v_mul_f32_e32 v66, 0xbfb8aa3b, v66
	v_exp_f32_e32 v66, v66
	v_add_f32_e32 v70, 1.0, v70
	v_add_f32_e32 v66, 1.0, v66
	v_add_f32_e32 v67, v164, v67
	v_mul_f32_e32 v67, 0xbfb8aa3b, v67
	v_rcp_f32_e32 v70, v70
	s_nop 0
	v_mul_f32_e32 v70, 0xc1000000, v70
	v_mul_f32_e32 v70, v165, v70
	v_mul_f32_e32 v70, 0x3fb8aa3b, v70
	v_exp_f32_e32 v70, v70
	ds_write_b32 v108, v70 offset:33984
	v_fma_f32 v70, -v70, v70, 1.0
	v_max_f32_e32 v70, 0, v70
	v_rcp_f32_e32 v66, v66
	ds_read_u16 v71, v104 offset:96
	v_exp_f32_e32 v67, v67
	s_waitcnt lgkmcnt(0)
	v_lshlrev_b32_e32 v71, 16, v71
	v_add_f32_e32 v67, 1.0, v67
	s_nop 0
	s_nop 1
	v_sqrt_f32_e32 v70, v70
	s_nop 0
	v_mul_f32_e32 v66, v66, v70
	v_mul_f32_e32 v66, v66, v71
	v_cvt_pk_bf16_f32 v66, v66, s0
	ds_write_b16 v115, v66 offset:38240
	v_add_f32_e32 v66, v163, v75
	v_mul_f32_e32 v66, 0xbfb8aa3b, v66
	v_exp_f32_e32 v66, v66
	s_nop 0
	v_add_f32_e32 v66, 1.0, v66
	s_nop 0
	v_rcp_f32_e32 v66, v66
	s_nop 0
	v_mul_f32_e32 v66, 0xc1000000, v66
	v_mul_f32_e32 v66, v165, v66
	v_mul_f32_e32 v66, 0x3fb8aa3b, v66
	v_exp_f32_e32 v66, v66
	ds_write_b32 v110, v66 offset:33984
	v_fma_f32 v66, -v66, v66, 1.0
	v_max_f32_e32 v66, 0, v66
	v_rcp_f32_e32 v67, v67
	ds_read_u16 v70, v102 offset:96
	s_waitcnt lgkmcnt(0)
	v_lshlrev_b32_e32 v70, 16, v70
	s_nop 1
	s_nop 1
	v_sqrt_f32_e32 v66, v66
	s_nop 0
	v_mul_f32_e32 v66, v67, v66
	v_mul_f32_e32 v66, v66, v70
	v_cvt_pk_bf16_f32 v66, v66, s0
	ds_write_b16 v116, v66 offset:38240
	v_add_f32_e32 v66, v163, v76
	v_mul_f32_e32 v66, 0xbfb8aa3b, v66
	v_exp_f32_e32 v66, v66
	s_nop 0
	v_add_f32_e32 v66, 1.0, v66
	s_nop 0
	v_rcp_f32_e32 v66, v66
	v_add_f32_e32 v67, v164, v68
	v_mul_f32_e32 v67, 0xbfb8aa3b, v67
	v_exp_f32_e32 v67, v67
	v_mul_f32_e32 v66, 0xc1000000, v66
	v_mul_f32_e32 v66, v165, v66
	v_mul_f32_e32 v66, 0x3fb8aa3b, v66
	v_add_f32_e32 v67, 1.0, v67
	v_exp_f32_e32 v66, v66
	ds_write_b32 v112, v66 offset:33984
	v_fma_f32 v66, -v66, v66, 1.0
	v_max_f32_e32 v66, 0, v66
	v_rcp_f32_e32 v67, v67
	ds_read_u16 v68, v100 offset:96
	s_waitcnt lgkmcnt(0)
	v_lshlrev_b32_e32 v68, 16, v68
	s_nop 1
	s_nop 1
	v_sqrt_f32_e32 v66, v66
	s_nop 0
	v_mul_f32_e32 v66, v67, v66
	v_mul_f32_e32 v66, v66, v68
	v_cvt_pk_bf16_f32 v66, v66, s0
	ds_write_b16 v117, v66 offset:38240
	v_add_f32_e32 v66, v163, v77
	v_mul_f32_e32 v66, 0xbfb8aa3b, v66
	v_exp_f32_e32 v66, v66
	s_nop 0
	v_add_f32_e32 v66, 1.0, v66
	s_nop 0
	v_rcp_f32_e32 v66, v66
	v_add_f32_e32 v67, v164, v69
	v_mul_f32_e32 v67, 0xbfb8aa3b, v67
	v_exp_f32_e32 v67, v67
	v_mul_f32_e32 v66, 0xc1000000, v66
	v_mul_f32_e32 v66, v165, v66
	v_mul_f32_e32 v66, 0x3fb8aa3b, v66
	v_add_f32_e32 v67, 1.0, v67
	v_exp_f32_e32 v66, v66
	ds_write_b32 v114, v66 offset:33984
	v_fma_f32 v66, -v66, v66, 1.0
	v_max_f32_e32 v66, 0, v66
	v_rcp_f32_e32 v67, v67
	ds_read_u16 v68, v98 offset:96
	s_waitcnt lgkmcnt(0)
	v_lshlrev_b32_e32 v68, 16, v68
	s_nop 1
	s_nop 1
	v_sqrt_f32_e32 v66, v66
	s_nop 0
	v_mul_f32_e32 v66, v67, v66
	v_mul_f32_e32 v66, v66, v68
	v_cvt_pk_bf16_f32 v66, v66, s0
	ds_write_b16 v118, v66 offset:38240
	s_waitcnt lgkmcnt(0)
	ds_read_b32 v66, v107 offset:33792
	ds_read_u16 v67, v119 offset:38144
	ds_read_b32 v68, v120 offset:33792
	ds_read_u16 v69, v140 offset:38144
	s_waitcnt lgkmcnt(2)
	v_lshlrev_b32_e32 v67, 16, v67
	v_fmac_f32_e32 v67, v66, v166
	v_mul_f32_e32 v66, v167, v66
	s_waitcnt lgkmcnt(0)
	v_lshlrev_b32_e32 v69, 16, v69
	v_fmac_f32_e32 v69, v68, v67
	v_mul_f32_e32 v66, v66, v68
	ds_read_b32 v67, v121 offset:33792
	ds_read_u16 v68, v141 offset:38144
	s_waitcnt lgkmcnt(1)
	v_mul_f32_e32 v66, v66, v67
	s_waitcnt lgkmcnt(0)
	v_lshlrev_b32_e32 v68, 16, v68
	v_fmac_f32_e32 v68, v67, v69
	ds_read_b32 v67, v122 offset:33792
	ds_read_u16 v69, v142 offset:38144
	s_waitcnt lgkmcnt(1)
	v_mul_f32_e32 v66, v66, v67
	s_waitcnt lgkmcnt(0)
	v_lshlrev_b32_e32 v69, 16, v69
	v_fmac_f32_e32 v69, v67, v68
	ds_read_b32 v67, v123 offset:33792
	ds_read_u16 v68, v143 offset:38144
	s_waitcnt lgkmcnt(1)
	v_mul_f32_e32 v66, v66, v67
	s_waitcnt lgkmcnt(0)
	v_lshlrev_b32_e32 v68, 16, v68
	v_fmac_f32_e32 v68, v67, v69
	ds_read_b32 v67, v124 offset:33792
	ds_read_u16 v69, v144 offset:38144
	s_waitcnt lgkmcnt(1)
	v_mul_f32_e32 v66, v66, v67
	s_waitcnt lgkmcnt(0)
	v_lshlrev_b32_e32 v69, 16, v69
	v_fmac_f32_e32 v69, v67, v68
	ds_read_b32 v67, v125 offset:33792
	ds_read_u16 v68, v145 offset:38144
	s_waitcnt lgkmcnt(1)
	v_mul_f32_e32 v66, v66, v67
	s_waitcnt lgkmcnt(0)
	v_lshlrev_b32_e32 v68, 16, v68
	v_fmac_f32_e32 v68, v67, v69
	ds_read_b32 v67, v126 offset:33792
	ds_read_u16 v69, v146 offset:38144
	s_waitcnt lgkmcnt(1)
	v_mul_f32_e32 v66, v66, v67
	s_waitcnt lgkmcnt(0)
	v_lshlrev_b32_e32 v69, 16, v69
	v_fmac_f32_e32 v69, v67, v68
	ds_read_b32 v67, v127 offset:33792
	ds_read_u16 v68, v147 offset:38144
	s_waitcnt lgkmcnt(1)
	v_mul_f32_e32 v66, v66, v67
	s_waitcnt lgkmcnt(0)
	v_lshlrev_b32_e32 v68, 16, v68
	v_fmac_f32_e32 v68, v67, v69
	ds_read_b32 v67, v128 offset:33792
	ds_read_u16 v69, v148 offset:38144
	s_waitcnt lgkmcnt(1)
	v_mul_f32_e32 v66, v66, v67
	s_waitcnt lgkmcnt(0)
	v_lshlrev_b32_e32 v69, 16, v69
	v_fmac_f32_e32 v69, v67, v68
	ds_read_b32 v67, v129 offset:33792
	ds_read_u16 v68, v149 offset:38144
	s_waitcnt lgkmcnt(1)
	v_mul_f32_e32 v66, v66, v67
	s_waitcnt lgkmcnt(0)
	v_lshlrev_b32_e32 v68, 16, v68
	v_fmac_f32_e32 v68, v67, v69
	ds_read_b32 v67, v130 offset:33792
	ds_read_u16 v69, v150 offset:38144
	s_waitcnt lgkmcnt(1)
	v_mul_f32_e32 v66, v66, v67
	s_waitcnt lgkmcnt(0)
	v_lshlrev_b32_e32 v69, 16, v69
	v_fmac_f32_e32 v69, v67, v68
	ds_read_b32 v67, v131 offset:33792
	ds_read_u16 v68, v151 offset:38144
	s_waitcnt lgkmcnt(1)
	v_mul_f32_e32 v66, v66, v67
	s_waitcnt lgkmcnt(0)
	v_lshlrev_b32_e32 v68, 16, v68
	v_fmac_f32_e32 v68, v67, v69
	ds_read_b32 v67, v132 offset:33792
	ds_read_u16 v69, v152 offset:38144
	s_waitcnt lgkmcnt(1)
	v_mul_f32_e32 v66, v66, v67
	s_waitcnt lgkmcnt(0)
	v_lshlrev_b32_e32 v69, 16, v69
	v_fmac_f32_e32 v69, v67, v68
	ds_read_b32 v67, v133 offset:33792
	ds_read_u16 v68, v153 offset:38144
	s_waitcnt lgkmcnt(1)
	v_mul_f32_e32 v66, v66, v67
	s_waitcnt lgkmcnt(0)
	v_lshlrev_b32_e32 v68, 16, v68
	v_fmac_f32_e32 v68, v67, v69
	ds_read_b32 v67, v134 offset:33792
	ds_read_u16 v69, v154 offset:38144
	s_waitcnt lgkmcnt(0)
	s_waitcnt lgkmcnt(1)
	v_mul_f32_e32 v167, v66, v67
	s_waitcnt lgkmcnt(0)
	v_lshlrev_b32_e32 v166, 16, v69
	v_fmac_f32_e32 v166, v67, v68
	s_cbranch_scc1 .LBB0_466
	s_and_b32 s0, s17, 0xffffffc0
	s_add_i32 s0, s0, s14
	s_or_b32 s0, s0, s18
	s_ashr_i32 s1, s0, 31
	s_lshl_b64 s[0:1], s[0:1], 10
	v_lshl_or_b32 v0, v94, 2, s0
	v_readlane_b32 s0, v254, 27
	v_mov_b32_e32 v1, s1
	s_add_i32 s17, s17, s26
	s_add_i32 s16, s16, s26
	s_add_i32 s15, s15, s0
	v_lshl_add_u64 v[2:3], s[6:7], 0, v[0:1]
	v_lshl_add_u64 v[0:1], s[8:9], 0, v[0:1]
	s_cmpk_gt_i32 s17, 0x1ff
	global_store_dword v[2:3], v167, off
	global_store_dword v[0:1], v166, off
	s_barrier
	s_cbranch_scc0 .LBB0_435

; __device__ __forceinline__ bf16_t f2bf(float f) { return (bf16_t)(cvt_pk_bf16(f, 0.f) & 0xffffu); }
; __device__ __forceinline__ float bf2f(bf16_t b) { return __uint_as_float(((unsigned)b) << 16); }
; __device__ __forceinline__ float sigmoidf_(float x) { return 1.0f / (1.0f + __expf(-x)); }
; template <bool FINAL>
; __device__ __forceinline__ void lru_item(const Ctx& C, int l, int item) {
;     ...
;             for (int dt = 0; dt < 4; ++dt) {
;                 f32x4 Da = {0.f, 0.f, 0.f, 0.f}, Dx = {0.f, 0.f, 0.f, 0.f};
;                 Da = __builtin_amdgcn_mfma_f32_16x16x32_bf16(xa0, Bw[0][dt][0], Da, 0, 0, 0); Da = __builtin_amdgcn_mfma_f32_16x16x32_bf16(xa1, Bw[0][dt][1], Da, 0, 0, 0);
;                 Dx = __builtin_amdgcn_mfma_f32_16x16x32_bf16(xa0, Bw[1][dt][0], Dx, 0, 0, 0); Dx = __builtin_amdgcn_mfma_f32_16x16x32_bf16(xa1, Bw[1][dt][1], Dx, 0, 0, 0);
; #pragma unroll
;                 for (int r = 0; r < 4; ++r) { const int tloc = 4 * quad + r, d = 16 * dt + fr;
;                     const float rg = sigmoidf_(Da[r] + bav[dt]), ig = sigmoidf_(Dx[r] + bxv[dt]), la = -8.0f * rg * spv[dt], a = __expf(la);
;                     const float x = bf2f(xc[(16 * tt + tloc) * XCP + n * 64 + d]);
;                     Al[tloc * 68 + d] = a; Ul[tloc * 68 + d] = f2bf(sqrtf(fmaxf(1.0f - a * a, 0.f)) * ig * x); }
.LBB0_681:
	s_and_b64 s[0:1], s[4:5], exec
	s_cselect_b32 s0, s9, s51
	s_lshl_b32 s52, s0, 4
	v_or_b32_e32 v66, s52, v97
	v_mad_u64_u32 v[66:67], s[0:1], v66, s58, v[96:97]
	ds_read_b128 v[70:73], v66
	ds_read_b128 v[66:69], v66 offset:64
	s_add_i32 s9, s9, 1
	s_add_i32 s51, s51, -1
	s_waitcnt lgkmcnt(1)
	v_mfma_f32_16x16x32_bf16 v[74:77], v[70:73], v[0:3], 0
	s_waitcnt lgkmcnt(0)
	v_mfma_f32_16x16x32_bf16 v[74:77], v[66:69], v[16:19], v[74:77]
	v_mfma_f32_16x16x32_bf16 v[104:107], v[70:73], v[32:35], 0
	v_mfma_f32_16x16x32_bf16 v[174:177], v[66:69], v[48:51], v[104:107]
	s_nop 5
	v_add_f32_e32 v74, v64, v74
	v_mul_f32_e32 v74, 0xbfb8aa3b, v74
	v_exp_f32_e32 v74, v74
	s_nop 0
	v_add_f32_e32 v74, 1.0, v74
	s_nop 0
	v_rcp_f32_e32 v74, v74
	v_add_f32_e32 v104, v162, v174
	v_mul_f32_e32 v104, 0xbfb8aa3b, v104
	v_exp_f32_e32 v104, v104
	v_mul_f32_e32 v74, 0xc1000000, v74
	v_mul_f32_e32 v74, v163, v74
	v_mul_f32_e32 v74, 0x3fb8aa3b, v74
	v_add_f32_e32 v104, 1.0, v104
	v_exp_f32_e32 v74, v74
	ds_write_b32 v114, v74 offset:33792
	v_fma_f32 v74, -v74, v74, 1.0
	v_max_f32_e32 v74, 0, v74
	v_rcp_f32_e32 v104, v104
	v_or_b32_e32 v105, s52, v112
	v_mad_u64_u32 v[110:111], s[0:1], v105, s58, v[98:99]
	ds_read_u16 v105, v110
	s_waitcnt lgkmcnt(0)
	v_lshlrev_b32_e32 v105, 16, v105
	s_nop 1
	v_sqrt_f32_e32 v74, v74
	s_nop 0
	v_mul_f32_e32 v74, v104, v74
	v_mul_f32_e32 v74, v74, v105
	v_cvt_pk_bf16_f32 v74, v74, s0
	ds_write_b16 v87, v74 offset:38144
	v_add_f32_e32 v74, v64, v75
	v_mul_f32_e32 v74, 0xbfb8aa3b, v74
	v_exp_f32_e32 v74, v74
	s_nop 0
	v_add_f32_e32 v74, 1.0, v74
	s_nop 0
	v_rcp_f32_e32 v74, v74
	v_add_f32_e32 v75, v162, v175
	v_mul_f32_e32 v75, 0xbfb8aa3b, v75
	v_exp_f32_e32 v75, v75
	v_mul_f32_e32 v74, 0xc1000000, v74
	v_mul_f32_e32 v74, v163, v74
	v_mul_f32_e32 v74, 0x3fb8aa3b, v74
	v_add_f32_e32 v75, 1.0, v75
	v_exp_f32_e32 v74, v74
	ds_write_b32 v116, v74 offset:33792
	v_fma_f32 v74, -v74, v74, 1.0
	v_max_f32_e32 v74, 0, v74
	v_rcp_f32_e32 v75, v75
	v_or_b32_e32 v104, s52, v115
	v_mad_u64_u32 v[108:109], s[0:1], v104, s58, v[98:99]
	ds_read_u16 v104, v108
	s_waitcnt lgkmcnt(0)
	v_lshlrev_b32_e32 v104, 16, v104
	s_nop 1
	v_sqrt_f32_e32 v74, v74
	s_nop 0
	v_mul_f32_e32 v74, v75, v74
	v_mul_f32_e32 v74, v74, v104
	v_cvt_pk_bf16_f32 v74, v74, s0
	ds_write_b16 v144, v74 offset:38144
	v_add_f32_e32 v74, v64, v76
	v_mul_f32_e32 v74, 0xbfb8aa3b, v74
	v_exp_f32_e32 v74, v74
	s_nop 0
	v_add_f32_e32 v74, 1.0, v74
	s_nop 0
	v_rcp_f32_e32 v74, v74
	v_add_f32_e32 v75, v162, v176
	v_mul_f32_e32 v75, 0xbfb8aa3b, v75
	v_exp_f32_e32 v75, v75
	v_mul_f32_e32 v74, 0xc1000000, v74
	v_mul_f32_e32 v74, v163, v74
	v_mul_f32_e32 v74, 0x3fb8aa3b, v74
	v_add_f32_e32 v75, 1.0, v75
	v_exp_f32_e32 v74, v74
	ds_write_b32 v118, v74 offset:33792
	v_fma_f32 v74, -v74, v74, 1.0
	v_max_f32_e32 v74, 0, v74
	v_rcp_f32_e32 v75, v75
	v_or_b32_e32 v76, s52, v117
	v_mad_u64_u32 v[106:107], s[0:1], v76, s58, v[98:99]
	ds_read_u16 v76, v106
	s_waitcnt lgkmcnt(0)
	v_lshlrev_b32_e32 v76, 16, v76
	s_nop 1
	v_sqrt_f32_e32 v74, v74
	s_nop 0
	v_mul_f32_e32 v74, v75, v74
	v_mul_f32_e32 v74, v74, v76
	v_cvt_pk_bf16_f32 v74, v74, s0
	ds_write_b16 v145, v74 offset:38144
	v_add_f32_e32 v74, v64, v77
	v_mul_f32_e32 v74, 0xbfb8aa3b, v74
	v_exp_f32_e32 v74, v74
	s_nop 0
	v_add_f32_e32 v74, 1.0, v74
	s_nop 0
	v_rcp_f32_e32 v74, v74
	v_add_f32_e32 v75, v162, v177
	v_mul_f32_e32 v75, 0xbfb8aa3b, v75
	v_exp_f32_e32 v75, v75
	v_mul_f32_e32 v74, 0xc1000000, v74
	v_mul_f32_e32 v74, v163, v74
	v_mul_f32_e32 v74, 0x3fb8aa3b, v74
	v_add_f32_e32 v75, 1.0, v75
	v_exp_f32_e32 v74, v74
	v_mfma_f32_16x16x32_bf16 v[174:177], v[70:73], v[36:39], 0
	ds_write_b32 v120, v74 offset:33792
	v_fma_f32 v74, -v74, v74, 1.0
	v_max_f32_e32 v74, 0, v74
	v_rcp_f32_e32 v75, v75
	v_or_b32_e32 v76, s52, v119
	v_mad_u64_u32 v[104:105], s[0:1], v76, s58, v[98:99]
	ds_read_u16 v76, v104
	v_mfma_f32_16x16x32_bf16 v[174:177], v[66:69], v[52:55], v[174:177]
	s_waitcnt lgkmcnt(0)
	v_lshlrev_b32_e32 v76, 16, v76
	s_nop 1
	v_sqrt_f32_e32 v74, v74
	s_nop 0
	v_mul_f32_e32 v74, v75, v74
	v_mul_f32_e32 v74, v74, v76
	v_cvt_pk_bf16_f32 v74, v74, s0
	ds_write_b16 v146, v74 offset:38144
	v_mfma_f32_16x16x32_bf16 v[74:77], v[70:73], v[4:7], 0
	v_mfma_f32_16x16x32_bf16 v[74:77], v[66:69], v[20:23], v[74:77]
	s_nop 7
	v_add_f32_e32 v74, v164, v74
	v_mul_f32_e32 v74, 0xbfb8aa3b, v74
	v_exp_f32_e32 v74, v74
	s_nop 0
	v_add_f32_e32 v74, 1.0, v74
	s_nop 0
	v_rcp_f32_e32 v74, v74
	v_add_f32_e32 v105, v165, v174
	v_mul_f32_e32 v105, 0xbfb8aa3b, v105
	v_exp_f32_e32 v105, v105
	v_mul_f32_e32 v74, 0xc1000000, v74
	v_mul_f32_e32 v74, v166, v74
	v_mul_f32_e32 v74, 0x3fb8aa3b, v74
	v_add_f32_e32 v105, 1.0, v105
	v_exp_f32_e32 v74, v74
	ds_write_b32 v114, v74 offset:33856
	v_fma_f32 v74, -v74, v74, 1.0
	v_max_f32_e32 v74, 0, v74
	v_rcp_f32_e32 v105, v105
	ds_read_u16 v107, v110 offset:32
	s_waitcnt lgkmcnt(0)
	v_lshlrev_b32_e32 v107, 16, v107
	s_nop 1
	s_nop 1
	v_sqrt_f32_e32 v74, v74
	s_nop 0
	v_mul_f32_e32 v74, v105, v74
	v_mul_f32_e32 v74, v74, v107
	v_cvt_pk_bf16_f32 v74, v74, s0
	ds_write_b16 v121, v74 offset:38176
	v_add_f32_e32 v74, v164, v75
	v_mul_f32_e32 v74, 0xbfb8aa3b, v74
	v_exp_f32_e32 v74, v74
	s_nop 0
	v_add_f32_e32 v74, 1.0, v74
	s_nop 0
	v_rcp_f32_e32 v74, v74
	v_add_f32_e32 v75, v165, v175
	v_mul_f32_e32 v75, 0xbfb8aa3b, v75
	v_exp_f32_e32 v75, v75
	v_mul_f32_e32 v74, 0xc1000000, v74
	v_mul_f32_e32 v74, v166, v74
	v_mul_f32_e32 v74, 0x3fb8aa3b, v74
	v_add_f32_e32 v75, 1.0, v75
	v_exp_f32_e32 v74, v74
	ds_write_b32 v116, v74 offset:33856
	v_fma_f32 v74, -v74, v74, 1.0
	v_max_f32_e32 v74, 0, v74
	v_rcp_f32_e32 v75, v75
	ds_read_u16 v105, v108 offset:32
	s_waitcnt lgkmcnt(0)
; __device__ __forceinline__ bf16_t f2bf(float f) { return (bf16_t)(cvt_pk_bf16(f, 0.f) & 0xffffu); }
; __device__ __forceinline__ float bf2f(bf16_t b) { return __uint_as_float(((unsigned)b) << 16); }
; __device__ __forceinline__ float sigmoidf_(float x) { return 1.0f / (1.0f + __expf(-x)); }
; template <bool FINAL>
; __device__ __forceinline__ void lru_item(const Ctx& C, int l, int item) {
;     ...
;             for (int dt = 0; dt < 4; ++dt) {
;                 f32x4 Da = {0.f, 0.f, 0.f, 0.f}, Dx = {0.f, 0.f, 0.f, 0.f};
;                 Da = __builtin_amdgcn_mfma_f32_16x16x32_bf16(xa0, Bw[0][dt][0], Da, 0, 0, 0); Da = __builtin_amdgcn_mfma_f32_16x16x32_bf16(xa1, Bw[0][dt][1], Da, 0, 0, 0);
;                 Dx = __builtin_amdgcn_mfma_f32_16x16x32_bf16(xa0, Bw[1][dt][0], Dx, 0, 0, 0); Dx = __builtin_amdgcn_mfma_f32_16x16x32_bf16(xa1, Bw[1][dt][1], Dx, 0, 0, 0);
; #pragma unroll
;                 for (int r = 0; r < 4; ++r) { const int tloc = 4 * quad + r, d = 16 * dt + fr;
;                     const float rg = sigmoidf_(Da[r] + bav[dt]), ig = sigmoidf_(Dx[r] + bxv[dt]), la = -8.0f * rg * spv[dt], a = __expf(la);
;                     const float x = bf2f(xc[(16 * tt + tloc) * XCP + n * 64 + d]);
;                     Al[tloc * 68 + d] = a; Ul[tloc * 68 + d] = f2bf(sqrtf(fmaxf(1.0f - a * a, 0.f)) * ig * x); }
	v_lshlrev_b32_e32 v105, 16, v105
	s_nop 1
	s_nop 1
	v_sqrt_f32_e32 v74, v74
	s_nop 0
	v_mul_f32_e32 v74, v75, v74
	v_mul_f32_e32 v74, v74, v105
	v_cvt_pk_bf16_f32 v74, v74, s0
	ds_write_b16 v122, v74 offset:38176
	v_add_f32_e32 v74, v164, v76
	v_mul_f32_e32 v74, 0xbfb8aa3b, v74
	v_exp_f32_e32 v74, v74
	s_nop 0
	v_add_f32_e32 v74, 1.0, v74
	s_nop 0
	v_rcp_f32_e32 v74, v74
	v_add_f32_e32 v75, v165, v176
	v_mul_f32_e32 v75, 0xbfb8aa3b, v75
	v_exp_f32_e32 v75, v75
	v_mul_f32_e32 v74, 0xc1000000, v74
	v_mul_f32_e32 v74, v166, v74
	v_mul_f32_e32 v74, 0x3fb8aa3b, v74
	v_add_f32_e32 v75, 1.0, v75
	v_exp_f32_e32 v74, v74
	ds_write_b32 v118, v74 offset:33856
	v_fma_f32 v74, -v74, v74, 1.0
	v_max_f32_e32 v74, 0, v74
	v_rcp_f32_e32 v75, v75
	ds_read_u16 v76, v106 offset:32
	s_waitcnt lgkmcnt(0)
	v_lshlrev_b32_e32 v76, 16, v76
	s_nop 1
	s_nop 1
	v_sqrt_f32_e32 v74, v74
	s_nop 0
	v_mul_f32_e32 v74, v75, v74
	v_mul_f32_e32 v74, v74, v76
	v_cvt_pk_bf16_f32 v74, v74, s0
	ds_write_b16 v123, v74 offset:38176
	v_add_f32_e32 v74, v164, v77
	v_mul_f32_e32 v74, 0xbfb8aa3b, v74
	v_exp_f32_e32 v74, v74
	s_nop 0
	v_add_f32_e32 v74, 1.0, v74
	s_nop 0
	v_rcp_f32_e32 v74, v74
	v_add_f32_e32 v75, v165, v177
	v_mul_f32_e32 v75, 0xbfb8aa3b, v75
	v_exp_f32_e32 v75, v75
	v_mul_f32_e32 v74, 0xc1000000, v74
	v_mul_f32_e32 v74, v166, v74
	v_mul_f32_e32 v74, 0x3fb8aa3b, v74
	v_add_f32_e32 v75, 1.0, v75
	v_exp_f32_e32 v74, v74
	v_mfma_f32_16x16x32_bf16 v[174:177], v[70:73], v[40:43], 0
	ds_write_b32 v120, v74 offset:33856
	v_fma_f32 v74, -v74, v74, 1.0
	v_max_f32_e32 v74, 0, v74
	v_rcp_f32_e32 v75, v75
	ds_read_u16 v76, v104 offset:32
	v_mfma_f32_16x16x32_bf16 v[174:177], v[66:69], v[56:59], v[174:177]
	s_waitcnt lgkmcnt(0)
	v_lshlrev_b32_e32 v76, 16, v76
	s_nop 1
	s_nop 1
	v_sqrt_f32_e32 v74, v74
	s_nop 0
	v_mul_f32_e32 v74, v75, v74
	v_mul_f32_e32 v74, v74, v76
	v_cvt_pk_bf16_f32 v74, v74, s0
	ds_write_b16 v124, v74 offset:38176
	v_mfma_f32_16x16x32_bf16 v[74:77], v[70:73], v[8:11], 0
	v_mfma_f32_16x16x32_bf16 v[74:77], v[66:69], v[24:27], v[74:77]
	s_nop 7
	v_add_f32_e32 v74, v167, v74
	v_mul_f32_e32 v74, 0xbfb8aa3b, v74
	v_exp_f32_e32 v74, v74
	s_nop 0
	v_add_f32_e32 v74, 1.0, v74
	s_nop 0
	v_rcp_f32_e32 v74, v74
	v_add_f32_e32 v105, v168, v174
	v_mul_f32_e32 v105, 0xbfb8aa3b, v105
	v_exp_f32_e32 v105, v105
	v_mul_f32_e32 v74, 0xc1000000, v74
	v_mul_f32_e32 v74, v169, v74
	v_mul_f32_e32 v74, 0x3fb8aa3b, v74
	v_add_f32_e32 v105, 1.0, v105
	v_exp_f32_e32 v74, v74
	ds_write_b32 v114, v74 offset:33920
	v_fma_f32 v74, -v74, v74, 1.0
	v_max_f32_e32 v74, 0, v74
	v_rcp_f32_e32 v105, v105
	ds_read_u16 v107, v110 offset:64
	s_waitcnt lgkmcnt(0)
	v_lshlrev_b32_e32 v107, 16, v107
	s_nop 1
	s_nop 1
	v_sqrt_f32_e32 v74, v74
	s_nop 0
	v_mul_f32_e32 v74, v105, v74
	v_mul_f32_e32 v74, v74, v107
	v_cvt_pk_bf16_f32 v74, v74, s0
	ds_write_b16 v121, v74 offset:38208
	v_add_f32_e32 v74, v167, v75
	v_mul_f32_e32 v74, 0xbfb8aa3b, v74
	v_exp_f32_e32 v74, v74
	s_nop 0
	v_add_f32_e32 v74, 1.0, v74
	s_nop 0
	v_rcp_f32_e32 v74, v74
	v_add_f32_e32 v75, v168, v175
	v_mul_f32_e32 v75, 0xbfb8aa3b, v75
	v_exp_f32_e32 v75, v75
	v_mul_f32_e32 v74, 0xc1000000, v74
	v_mul_f32_e32 v74, v169, v74
	v_mul_f32_e32 v74, 0x3fb8aa3b, v74
	v_add_f32_e32 v75, 1.0, v75
	v_exp_f32_e32 v74, v74
	ds_write_b32 v116, v74 offset:33920
	v_fma_f32 v74, -v74, v74, 1.0
	v_max_f32_e32 v74, 0, v74
	v_rcp_f32_e32 v75, v75
	ds_read_u16 v105, v108 offset:64
	s_waitcnt lgkmcnt(0)
	v_lshlrev_b32_e32 v105, 16, v105
	s_nop 1
	s_nop 1
	v_sqrt_f32_e32 v74, v74
	s_nop 0
	v_mul_f32_e32 v74, v75, v74
	v_mul_f32_e32 v74, v74, v105
	v_cvt_pk_bf16_f32 v74, v74, s0
	ds_write_b16 v122, v74 offset:38208
	v_add_f32_e32 v74, v167, v76
	v_mul_f32_e32 v74, 0xbfb8aa3b, v74
	v_exp_f32_e32 v74, v74
	s_nop 0
	v_add_f32_e32 v74, 1.0, v74
	s_nop 0
	v_rcp_f32_e32 v74, v74
	v_add_f32_e32 v75, v168, v176
	v_mul_f32_e32 v75, 0xbfb8aa3b, v75
	v_exp_f32_e32 v75, v75
	v_mul_f32_e32 v74, 0xc1000000, v74
	v_mul_f32_e32 v74, v169, v74
	v_mul_f32_e32 v74, 0x3fb8aa3b, v74
	v_add_f32_e32 v75, 1.0, v75
	v_exp_f32_e32 v74, v74
	ds_write_b32 v118, v74 offset:33920
	v_fma_f32 v74, -v74, v74, 1.0
	v_max_f32_e32 v74, 0, v74
	v_rcp_f32_e32 v75, v75
	ds_read_u16 v76, v106 offset:64
	s_waitcnt lgkmcnt(0)
	v_lshlrev_b32_e32 v76, 16, v76
	s_nop 1
	s_nop 1
	v_sqrt_f32_e32 v74, v74
	s_nop 0
	v_mul_f32_e32 v74, v75, v74
	v_mul_f32_e32 v74, v74, v76
	v_cvt_pk_bf16_f32 v74, v74, s0
	ds_write_b16 v123, v74 offset:38208
	v_add_f32_e32 v74, v167, v77
	v_mul_f32_e32 v74, 0xbfb8aa3b, v74
	v_exp_f32_e32 v74, v74
	s_nop 0
	v_add_f32_e32 v74, 1.0, v74
	s_nop 0
	v_rcp_f32_e32 v74, v74
	v_add_f32_e32 v75, v168, v177
	v_mul_f32_e32 v75, 0xbfb8aa3b, v75
	v_exp_f32_e32 v75, v75
	v_mul_f32_e32 v74, 0xc1000000, v74
	v_mul_f32_e32 v74, v169, v74
	v_mul_f32_e32 v74, 0x3fb8aa3b, v74
	v_add_f32_e32 v75, 1.0, v75
	v_exp_f32_e32 v74, v74
	ds_write_b32 v120, v74 offset:33920
	v_fma_f32 v74, -v74, v74, 1.0
	v_max_f32_e32 v74, 0, v74
	v_rcp_f32_e32 v75, v75
	ds_read_u16 v76, v104 offset:64
	s_waitcnt lgkmcnt(0)
	v_lshlrev_b32_e32 v76, 16, v76
	s_nop 1
	s_nop 1
	v_sqrt_f32_e32 v74, v74
	s_nop 0
	v_mul_f32_e32 v74, v75, v74
	v_mul_f32_e32 v74, v74, v76
	v_cvt_pk_bf16_f32 v74, v74, s0
	ds_write_b16 v124, v74 offset:38208
	v_mfma_f32_16x16x32_bf16 v[74:77], v[70:73], v[12:15], 0
	v_mfma_f32_16x16x32_bf16 v[74:77], v[66:69], v[28:31], v[74:77]
	v_mfma_f32_16x16x32_bf16 v[70:73], v[70:73], v[44:47], 0
	v_mfma_f32_16x16x32_bf16 v[66:69], v[66:69], v[60:63], v[70:73]
	s_waitcnt vmcnt(2)
	s_nop 5
	v_add_f32_e32 v70, v170, v74
	v_mul_f32_e32 v70, 0xbfb8aa3b, v70
	v_exp_f32_e32 v70, v70
	s_waitcnt vmcnt(1)
; __device__ __forceinline__ bf16_t f2bf(float f) { return (bf16_t)(cvt_pk_bf16(f, 0.f) & 0xffffu); }
; __device__ __forceinline__ float bf2f(bf16_t b) { return __uint_as_float(((unsigned)b) << 16); }
; __device__ __forceinline__ float sigmoidf_(float x) { return 1.0f / (1.0f + __expf(-x)); }
; __device__ __forceinline__ void wave_lds_fence() { asm volatile("s_waitcnt lgkmcnt(0)" ::: "memory"); __builtin_amdgcn_wave_barrier(); }
; template <bool FINAL>
; __device__ __forceinline__ void lru_item(const Ctx& C, int l, int item) {
;     ...
;             for (int dt = 0; dt < 4; ++dt) {
;                 f32x4 Da = {0.f, 0.f, 0.f, 0.f}, Dx = {0.f, 0.f, 0.f, 0.f};
;                 Da = __builtin_amdgcn_mfma_f32_16x16x32_bf16(xa0, Bw[0][dt][0], Da, 0, 0, 0); Da = __builtin_amdgcn_mfma_f32_16x16x32_bf16(xa1, Bw[0][dt][1], Da, 0, 0, 0);
;                 Dx = __builtin_amdgcn_mfma_f32_16x16x32_bf16(xa0, Bw[1][dt][0], Dx, 0, 0, 0); Dx = __builtin_amdgcn_mfma_f32_16x16x32_bf16(xa1, Bw[1][dt][1], Dx, 0, 0, 0);
; #pragma unroll
;                 for (int r = 0; r < 4; ++r) { const int tloc = 4 * quad + r, d = 16 * dt + fr;
;                     const float rg = sigmoidf_(Da[r] + bav[dt]), ig = sigmoidf_(Dx[r] + bxv[dt]), la = -8.0f * rg * spv[dt], a = __expf(la);
;                     const float x = bf2f(xc[(16 * tt + tloc) * XCP + n * 64 + d]);
;                     Al[tloc * 68 + d] = a; Ul[tloc * 68 + d] = f2bf(sqrtf(fmaxf(1.0f - a * a, 0.f)) * ig * x); }
;             }
;             wave_lds_fence();
; #pragma unroll
;             for (int j = 0; j < 16; ++j) { const int tloc = z ? 15 - j : j;
;                 const float a = Al[tloc * 68 + lane], u = bf2f(Ul[tloc * 68 + lane]);
;                 h = fmaf(a, h, u); Ap *= a;
;                 if (FINAL) Hz[(16 * tt + tloc) * 256 + n * 64 + lane] = f2bf(h); }
	v_add_f32_e32 v66, v171, v66
	v_mul_f32_e32 v66, 0xbfb8aa3b, v66
	v_exp_f32_e32 v66, v66
	v_add_f32_e32 v70, 1.0, v70
	v_add_f32_e32 v66, 1.0, v66
	v_add_f32_e32 v67, v171, v67
	v_mul_f32_e32 v67, 0xbfb8aa3b, v67
	v_rcp_f32_e32 v70, v70
	s_nop 0
	v_mul_f32_e32 v70, 0xc1000000, v70
	v_mul_f32_e32 v70, v172, v70
	v_mul_f32_e32 v70, 0x3fb8aa3b, v70
	v_exp_f32_e32 v70, v70
	ds_write_b32 v114, v70 offset:33984
	v_fma_f32 v70, -v70, v70, 1.0
	v_max_f32_e32 v70, 0, v70
	v_rcp_f32_e32 v66, v66
	ds_read_u16 v71, v110 offset:96
	v_exp_f32_e32 v67, v67
	s_waitcnt lgkmcnt(0)
	v_lshlrev_b32_e32 v71, 16, v71
	v_add_f32_e32 v67, 1.0, v67
	s_nop 0
	s_nop 1
	v_sqrt_f32_e32 v70, v70
	s_nop 0
	v_mul_f32_e32 v66, v66, v70
	v_mul_f32_e32 v66, v66, v71
	v_cvt_pk_bf16_f32 v66, v66, s0
	ds_write_b16 v121, v66 offset:38240
	v_add_f32_e32 v66, v170, v75
	v_mul_f32_e32 v66, 0xbfb8aa3b, v66
	v_exp_f32_e32 v66, v66
	s_nop 0
	v_add_f32_e32 v66, 1.0, v66
	s_nop 0
	v_rcp_f32_e32 v66, v66
	s_nop 0
	v_mul_f32_e32 v66, 0xc1000000, v66
	v_mul_f32_e32 v66, v172, v66
	v_mul_f32_e32 v66, 0x3fb8aa3b, v66
	v_exp_f32_e32 v66, v66
	ds_write_b32 v116, v66 offset:33984
	v_fma_f32 v66, -v66, v66, 1.0
	v_max_f32_e32 v66, 0, v66
	v_rcp_f32_e32 v67, v67
	ds_read_u16 v70, v108 offset:96
	s_waitcnt lgkmcnt(0)
	v_lshlrev_b32_e32 v70, 16, v70
	s_nop 1
	s_nop 1
	v_sqrt_f32_e32 v66, v66
	s_nop 0
	v_mul_f32_e32 v66, v67, v66
	v_mul_f32_e32 v66, v66, v70
	v_cvt_pk_bf16_f32 v66, v66, s0
	ds_write_b16 v122, v66 offset:38240
	v_add_f32_e32 v66, v170, v76
	v_mul_f32_e32 v66, 0xbfb8aa3b, v66
	v_exp_f32_e32 v66, v66
	s_nop 0
	v_add_f32_e32 v66, 1.0, v66
	s_nop 0
	v_rcp_f32_e32 v66, v66
	v_add_f32_e32 v67, v171, v68
	v_mul_f32_e32 v67, 0xbfb8aa3b, v67
	v_exp_f32_e32 v67, v67
	v_mul_f32_e32 v66, 0xc1000000, v66
	v_mul_f32_e32 v66, v172, v66
	v_mul_f32_e32 v66, 0x3fb8aa3b, v66
	v_add_f32_e32 v67, 1.0, v67
	v_exp_f32_e32 v66, v66
	ds_write_b32 v118, v66 offset:33984
	v_fma_f32 v66, -v66, v66, 1.0
	v_max_f32_e32 v66, 0, v66
	v_rcp_f32_e32 v67, v67
	ds_read_u16 v68, v106 offset:96
	s_waitcnt lgkmcnt(0)
	v_lshlrev_b32_e32 v68, 16, v68
	s_nop 1
	s_nop 1
	v_sqrt_f32_e32 v66, v66
	s_nop 0
	v_mul_f32_e32 v66, v67, v66
	v_mul_f32_e32 v66, v66, v68
	v_cvt_pk_bf16_f32 v66, v66, s0
	ds_write_b16 v123, v66 offset:38240
	v_add_f32_e32 v66, v170, v77
	v_mul_f32_e32 v66, 0xbfb8aa3b, v66
	v_exp_f32_e32 v66, v66
	s_nop 0
	v_add_f32_e32 v66, 1.0, v66
	s_nop 0
	v_rcp_f32_e32 v66, v66
	v_add_f32_e32 v67, v171, v69
	v_mul_f32_e32 v67, 0xbfb8aa3b, v67
	v_exp_f32_e32 v67, v67
	v_mul_f32_e32 v66, 0xc1000000, v66
	v_mul_f32_e32 v66, v172, v66
	v_mul_f32_e32 v66, 0x3fb8aa3b, v66
	v_add_f32_e32 v67, 1.0, v67
	v_exp_f32_e32 v66, v66
	ds_write_b32 v120, v66 offset:33984
	v_fma_f32 v66, -v66, v66, 1.0
	v_max_f32_e32 v66, 0, v66
	v_rcp_f32_e32 v67, v67
	ds_read_u16 v68, v104 offset:96
	s_waitcnt lgkmcnt(0)
	v_lshlrev_b32_e32 v68, 16, v68
	s_nop 1
	s_nop 1
	v_sqrt_f32_e32 v66, v66
	s_nop 0
	v_mul_f32_e32 v66, v67, v66
	v_mul_f32_e32 v66, v66, v68
	v_cvt_pk_bf16_f32 v66, v66, s0
	ds_write_b16 v124, v66 offset:38240
	s_waitcnt lgkmcnt(0)
	ds_read_b32 v67, v113 offset:33792
	ds_read_u16 v66, v125 offset:38144
	s_waitcnt lgkmcnt(0)
	v_lshlrev_b32_e32 v66, 16, v66
	s_waitcnt vmcnt(0)
	v_fmac_f32_e32 v66, v67, v173
	v_cvt_pk_bf16_f32 v67, v66, s0
	s_or_b32 s0, s52, s13
	v_lshl_add_u32 v68, s0, 9, v141
	ds_write_b16 v68, v67
	ds_read_b32 v68, v126 offset:33792
	ds_read_u16 v67, v147 offset:38144
	s_waitcnt lgkmcnt(0)
	v_lshlrev_b32_e32 v67, 16, v67
	v_fmac_f32_e32 v67, v68, v66
	v_cvt_pk_bf16_f32 v66, v67, s0
	s_or_b32 s0, s52, s14
	v_lshl_add_u32 v68, s0, 9, v141
	ds_write_b16 v68, v66
	ds_read_b32 v66, v127 offset:33792
	ds_read_u16 v68, v148 offset:38144
	s_waitcnt lgkmcnt(0)
	v_lshlrev_b32_e32 v68, 16, v68
	v_fmac_f32_e32 v68, v66, v67
	v_cvt_pk_bf16_f32 v66, v68, s0
	s_or_b32 s0, s52, s15
	v_lshl_add_u32 v67, s0, 9, v141
	ds_write_b16 v67, v66
	ds_read_b32 v66, v128 offset:33792
	ds_read_u16 v67, v149 offset:38144
	s_waitcnt lgkmcnt(0)
; __device__ __forceinline__ bf16_t f2bf(float f) { return (bf16_t)(cvt_pk_bf16(f, 0.f) & 0xffffu); }
; __device__ __forceinline__ float bf2f(bf16_t b) { return __uint_as_float(((unsigned)b) << 16); }
; __device__ __forceinline__ void wave_lds_fence() { asm volatile("s_waitcnt lgkmcnt(0)" ::: "memory"); __builtin_amdgcn_wave_barrier(); }
;     __device__ __forceinline__ bf16_t* bfp(size_t off) const { return (bf16_t*)(ws + off); }
;     __device__ __forceinline__ float* fp(size_t off) const { return (float*)(ws + off); }
; template <bool FINAL>
; __device__ __forceinline__ void lru_item(const Ctx& C, int l, int item) {
;     ...
; #pragma unroll
;             for (int j = 0; j < 16; ++j) { const int tloc = z ? 15 - j : j;
;                 const float a = Al[tloc * 68 + lane], u = bf2f(Ul[tloc * 68 + lane]);
;                 h = fmaf(a, h, u); Ap *= a;
;                 if (FINAL) Hz[(16 * tt + tloc) * 256 + n * 64 + lane] = f2bf(h); }
;             wave_lds_fence();
;         }
;         if (!FINAL) { C.fp(OFF_CARA)[cidx] = Ap; C.fp(OFF_CARH)[cidx] = h; }
;     }
;     if (FINAL) {
;         __syncthreads();
;         int ch = tid & 255; asm volatile("" : "+v"(ch)); const int zz = tid >> 8;
;         const bf16_t* gp = pb + (size_t)(b * SEQ + c * 64) * 512 + 256 + ch; bf16_t* yb = C.bfp(OFF_YB) + (size_t)(b * SEQ + c * 64) * 256 + ch;
	v_lshlrev_b32_e32 v67, 16, v67
	v_fmac_f32_e32 v67, v66, v68
	v_cvt_pk_bf16_f32 v66, v67, s0
	s_or_b32 s0, s52, s16
	v_lshl_add_u32 v68, s0, 9, v141
	ds_write_b16 v68, v66
	ds_read_b32 v66, v129 offset:33792
	ds_read_u16 v68, v150 offset:38144
	s_waitcnt lgkmcnt(0)
	v_lshlrev_b32_e32 v68, 16, v68
	v_fmac_f32_e32 v68, v66, v67
	v_cvt_pk_bf16_f32 v66, v68, s0
	s_or_b32 s0, s52, s17
	v_lshl_add_u32 v67, s0, 9, v141
	ds_write_b16 v67, v66
	ds_read_b32 v66, v130 offset:33792
	ds_read_u16 v67, v151 offset:38144
	s_waitcnt lgkmcnt(0)
	v_lshlrev_b32_e32 v67, 16, v67
	v_fmac_f32_e32 v67, v66, v68
	v_cvt_pk_bf16_f32 v66, v67, s0
	s_or_b32 s0, s52, s18
	v_lshl_add_u32 v68, s0, 9, v141
	ds_write_b16 v68, v66
	ds_read_b32 v66, v131 offset:33792
	ds_read_u16 v68, v152 offset:38144
	s_waitcnt lgkmcnt(0)
	v_lshlrev_b32_e32 v68, 16, v68
	v_fmac_f32_e32 v68, v66, v67
	v_cvt_pk_bf16_f32 v66, v68, s0
	s_or_b32 s0, s52, s19
	v_lshl_add_u32 v67, s0, 9, v141
	ds_write_b16 v67, v66
	ds_read_b32 v66, v132 offset:33792
	ds_read_u16 v67, v153 offset:38144
	s_waitcnt lgkmcnt(0)
	v_lshlrev_b32_e32 v67, 16, v67
	v_fmac_f32_e32 v67, v66, v68
	v_cvt_pk_bf16_f32 v66, v67, s0
	s_or_b32 s0, s52, s20
	v_lshl_add_u32 v68, s0, 9, v141
	ds_write_b16 v68, v66
	ds_read_b32 v66, v133 offset:33792
	ds_read_u16 v68, v154 offset:38144
	s_waitcnt lgkmcnt(0)
	v_lshlrev_b32_e32 v68, 16, v68
	v_fmac_f32_e32 v68, v66, v67
	v_cvt_pk_bf16_f32 v66, v68, s0
	s_or_b32 s0, s52, s21
	v_lshl_add_u32 v67, s0, 9, v141
	ds_write_b16 v67, v66
	ds_read_b32 v66, v134 offset:33792
	ds_read_u16 v67, v155 offset:38144
	s_waitcnt lgkmcnt(0)
	v_lshlrev_b32_e32 v67, 16, v67
	v_fmac_f32_e32 v67, v66, v68
	v_cvt_pk_bf16_f32 v66, v67, s0
	s_or_b32 s0, s52, s36
	v_lshl_add_u32 v68, s0, 9, v141
	ds_write_b16 v68, v66
	ds_read_b32 v66, v135 offset:33792
	ds_read_u16 v68, v156 offset:38144
	s_waitcnt lgkmcnt(0)
	v_lshlrev_b32_e32 v68, 16, v68
	v_fmac_f32_e32 v68, v66, v67
	v_cvt_pk_bf16_f32 v66, v68, s0
	s_or_b32 s0, s52, s38
	v_lshl_add_u32 v67, s0, 9, v141
	ds_write_b16 v67, v66
	ds_read_b32 v66, v136 offset:33792
	ds_read_u16 v67, v157 offset:38144
	s_waitcnt lgkmcnt(0)
	v_lshlrev_b32_e32 v67, 16, v67
	v_fmac_f32_e32 v67, v66, v68
	v_cvt_pk_bf16_f32 v66, v67, s0
	s_or_b32 s0, s52, s39
	v_lshl_add_u32 v68, s0, 9, v141
	ds_write_b16 v68, v66
	ds_read_b32 v66, v137 offset:33792
	ds_read_u16 v68, v158 offset:38144
	s_waitcnt lgkmcnt(0)
	v_lshlrev_b32_e32 v68, 16, v68
	v_fmac_f32_e32 v68, v66, v67
	v_cvt_pk_bf16_f32 v66, v68, s0
	s_or_b32 s0, s52, s42
	v_lshl_add_u32 v67, s0, 9, v141
	ds_write_b16 v67, v66
	ds_read_b32 v66, v138 offset:33792
	ds_read_u16 v67, v159 offset:38144
	s_waitcnt lgkmcnt(0)
	v_lshlrev_b32_e32 v67, 16, v67
	v_fmac_f32_e32 v67, v66, v68
	v_cvt_pk_bf16_f32 v66, v67, s0
	s_or_b32 s0, s52, s43
	v_lshl_add_u32 v68, s0, 9, v141
	ds_write_b16 v68, v66
	ds_read_b32 v68, v139 offset:33792
	ds_read_u16 v66, v160 offset:38144
	s_waitcnt lgkmcnt(0)
	v_lshlrev_b32_e32 v66, 16, v66
	v_fmac_f32_e32 v66, v68, v67
	v_cvt_pk_bf16_f32 v67, v66, s0
	s_or_b32 s0, s52, s44
	v_lshl_add_u32 v68, s0, 9, v141
	ds_write_b16 v68, v67
	ds_read_b32 v67, v140 offset:33792
	ds_read_u16 v68, v161 offset:38144
	s_waitcnt lgkmcnt(0)
	v_lshlrev_b32_e32 v173, 16, v68
	v_fmac_f32_e32 v173, v67, v66
	v_cvt_pk_bf16_f32 v66, v173, s0
	s_or_b32 s0, s52, s45
	v_lshl_add_u32 v67, s0, 9, v141
	ds_write_b16 v67, v66
	s_waitcnt lgkmcnt(0)
	s_cmp_eq_u32 s9, 4
	s_cbranch_scc0 .LBB0_681
	s_add_i32 s0, s8, s49
	s_ashr_i32 s1, s0, 31
	v_mov_b32_e32 v4, v99
	s_lshl_b64 s[8:9], s[0:1], 10
	s_lshl_b64 s[0:1], s[0:1], 9
	s_waitcnt lgkmcnt(0)
	s_barrier
	v_lshl_add_u64 v[0:1], v[100:101], 0, s[8:9]
	v_ashrrev_i32_e32 v5, 31, v4
	v_lshl_add_u64 v[2:3], v[102:103], 0, s[0:1]
	v_lshl_add_u32 v8, v4, 1, v143
	v_lshlrev_b64 v[4:5], 1, v[4:5]
	s_mov_b32 s0, 0

; __global__ void __launch_bounds__(NTHR, 2) fwd_megakernel(Params prm) {
;     ...
;         for (int it = bid * 8 + C.wave; it < 1024; it += G * 8) hgrn_pass3_item<0>(C, l, it);
;         __syncthreads();
;         for (int _m = 0; _m < REP_MIXC; ++_m) { for (int it = bid * 8 + C.wave; it < 2048; it += G * 8) hy_out_tr_item(C, it);
.LBB0_746:
	s_cmpk_lg_i32 s26, 0x100
	s_cbranch_scc1 .Lmy_otr_keep
	s_cmpk_lt_i32 s68, 0x400
	s_cselect_b32 s68, 0xc00, s68
	s_addk_i32 s68, 0xfc00

; __device__ __forceinline__ void wave_lds_fence() { asm volatile("s_waitcnt lgkmcnt(0)" ::: "memory"); __builtin_amdgcn_wave_barrier(); }
; __device__ __forceinline__ void hy_out_tr_item(const Ctx& C, int item) {
;     ...
; #pragma unroll 1
;     for (int c0 = 0; c0 < 64; c0 += 16) { bf16_t tv_[16];
; #pragma unroll
;         for (int q = 0; q < 16; ++q) tv_[q] = yct[(size_t)(cb * 64 + c0 + q) * M_TOK + tok0 + lane];
; #pragma unroll
;         for (int q = 0; q < 16; ++q) tile[(c0 + q) * 66 + lane] = tv_[q]; }
;     wave_lds_fence();
;     for (int tl = 0; tl < 64; ++tl) yc[(size_t)(tok0 + tl) * 256 + cb * 64 + lane] = tile[lane * 66 + tl];
.LBB0_749:
	v_add_co_u32_e32 v8, vcc, 0xfff10000, v4
	s_mov_b32 s7, 0xffff0000
	s_nop 0
	v_addc_co_u32_e32 v9, vcc, -1, v5, vcc
	global_load_ushort v7, v[8:9], off
	v_add_co_u32_e32 v8, vcc, 0xfff20000, v4
	s_add_i32 s6, s6, 16
	s_nop 0
	v_addc_co_u32_e32 v9, vcc, -1, v5, vcc
	global_load_ushort v10, v[8:9], off
	v_add_co_u32_e32 v8, vcc, 0xfff30000, v4
	s_cmp_lt_u32 s6, 48
	s_nop 0
	v_addc_co_u32_e32 v9, vcc, -1, v5, vcc
	global_load_ushort v11, v[8:9], off
	v_add_co_u32_e32 v8, vcc, 0xfff40000, v4
	s_nop 1
	v_addc_co_u32_e32 v9, vcc, -1, v5, vcc
	global_load_ushort v12, v[8:9], off
	v_add_co_u32_e32 v8, vcc, 0xfff50000, v4
	s_nop 1
	v_addc_co_u32_e32 v9, vcc, -1, v5, vcc
	global_load_ushort v13, v[8:9], off
	v_add_co_u32_e32 v8, vcc, 0xfff60000, v4
	s_nop 1
	v_addc_co_u32_e32 v9, vcc, -1, v5, vcc
	global_load_ushort v16, v[8:9], off
	v_add_co_u32_e32 v8, vcc, 0xfff70000, v4
	s_nop 1
	v_addc_co_u32_e32 v9, vcc, -1, v5, vcc
	global_load_ushort v17, v[8:9], off
	v_add_co_u32_e32 v8, vcc, 0xfff80000, v4
	s_nop 1
	v_addc_co_u32_e32 v9, vcc, -1, v5, vcc
	global_load_ushort v18, v[8:9], off
	v_add_co_u32_e32 v8, vcc, 0xfff90000, v4
	s_nop 1
	v_addc_co_u32_e32 v9, vcc, -1, v5, vcc
	global_load_ushort v19, v[8:9], off
	v_add_co_u32_e32 v8, vcc, 0xfffa0000, v4
	s_nop 1
	v_addc_co_u32_e32 v9, vcc, -1, v5, vcc
	global_load_ushort v20, v[8:9], off
	v_add_co_u32_e32 v8, vcc, 0xfffb0000, v4
	s_nop 1
	v_addc_co_u32_e32 v9, vcc, -1, v5, vcc
	global_load_ushort v21, v[8:9], off
	v_add_co_u32_e32 v8, vcc, 0xfffc0000, v4
	s_nop 1
	v_addc_co_u32_e32 v9, vcc, -1, v5, vcc
	global_load_ushort v22, v[8:9], off
	v_add_co_u32_e32 v8, vcc, 0xfffd0000, v4
	s_nop 1
	v_addc_co_u32_e32 v9, vcc, -1, v5, vcc
	global_load_ushort v23, v[8:9], off
	v_add_co_u32_e32 v8, vcc, 0xfffe0000, v4
	s_nop 1
	v_addc_co_u32_e32 v9, vcc, -1, v5, vcc
	global_load_ushort v24, v[8:9], off
	v_add_co_u32_e32 v8, vcc, s7, v4
	s_nop 1
	v_addc_co_u32_e32 v9, vcc, -1, v5, vcc
	global_load_ushort v8, v[8:9], off
	s_nop 0
	global_load_ushort v9, v[4:5], off
	v_lshl_add_u64 v[4:5], v[4:5], 0, s[12:13]
	s_waitcnt vmcnt(15)
	ds_write_b16 v6, v7
	s_waitcnt vmcnt(14)
	ds_write_b16 v6, v10 offset:132
	s_waitcnt vmcnt(13)
	ds_write_b16 v6, v11 offset:264
	s_waitcnt vmcnt(12)
	ds_write_b16 v6, v12 offset:396
	s_waitcnt vmcnt(11)
	ds_write_b16 v6, v13 offset:528
	s_waitcnt vmcnt(10)
	ds_write_b16 v6, v16 offset:660
	s_waitcnt vmcnt(9)
	ds_write_b16 v6, v17 offset:792
	s_waitcnt vmcnt(8)
	ds_write_b16 v6, v18 offset:924
	s_waitcnt vmcnt(7)
	ds_write_b16 v6, v19 offset:1056
	s_waitcnt vmcnt(6)
	ds_write_b16 v6, v20 offset:1188
	s_waitcnt vmcnt(5)
	ds_write_b16 v6, v21 offset:1320
	s_waitcnt vmcnt(4)
	ds_write_b16 v6, v22 offset:1452
	s_waitcnt vmcnt(3)
	ds_write_b16 v6, v23 offset:1584
	s_waitcnt vmcnt(2)
	ds_write_b16 v6, v24 offset:1716
	s_waitcnt vmcnt(1)
	ds_write_b16 v6, v8 offset:1848
	s_waitcnt vmcnt(0)
	ds_write_b16 v6, v9 offset:1980
	v_add_u32_e32 v6, 0x840, v6
	s_cbranch_scc1 .LBB0_749
	s_waitcnt lgkmcnt(0)
	ds_read2_b32 v[16:17], v14 offset1:1
	v_lshl_add_u64 v[4:5], s[4:5], 1, v[0:1]
	s_or_b32 s4, s0, 3
	s_or_b32 s6, s0, 2
	s_or_b32 s8, s0, 1
	s_ashr_i32 s9, s8, 31
	s_ashr_i32 s7, s6, 31
	s_ashr_i32 s5, s4, 31
	s_lshl_b64 s[10:11], s[0:1], 9
	s_lshl_b64 s[4:5], s[4:5], 9
	s_lshl_b64 s[6:7], s[6:7], 9
	s_lshl_b64 s[8:9], s[8:9], 9
	v_lshl_add_u64 v[6:7], v[4:5], 0, s[10:11]
	v_lshl_add_u64 v[8:9], v[4:5], 0, s[8:9]
	v_lshl_add_u64 v[10:11], v[4:5], 0, s[6:7]
	v_lshl_add_u64 v[12:13], v[4:5], 0, s[4:5]
	s_waitcnt lgkmcnt(0)
	global_store_short v[6:7], v16, off
	global_store_short_d16_hi v[8:9], v16, off
	global_store_short v[10:11], v17, off
	global_store_short_d16_hi v[12:13], v17, off
	ds_read2_b32 v[16:17], v14 offset0:2 offset1:3
	s_or_b32 s10, s0, 4
	s_or_b32 s4, s0, 7
	s_or_b32 s6, s0, 6
	s_or_b32 s8, s0, 5
	s_ashr_i32 s11, s10, 31
	s_ashr_i32 s9, s8, 31
	s_ashr_i32 s7, s6, 31
	s_ashr_i32 s5, s4, 31
	s_lshl_b64 s[10:11], s[10:11], 9
	s_lshl_b64 s[4:5], s[4:5], 9
	s_lshl_b64 s[6:7], s[6:7], 9
	s_lshl_b64 s[8:9], s[8:9], 9
	v_lshl_add_u64 v[6:7], v[4:5], 0, s[10:11]
	v_lshl_add_u64 v[8:9], v[4:5], 0, s[8:9]
	v_lshl_add_u64 v[10:11], v[4:5], 0, s[6:7]
	v_lshl_add_u64 v[12:13], v[4:5], 0, s[4:5]
	s_waitcnt lgkmcnt(0)
	global_store_short v[6:7], v16, off
	global_store_short_d16_hi v[8:9], v16, off
	global_store_short v[10:11], v17, off
	global_store_short_d16_hi v[12:13], v17, off
	ds_read2_b32 v[16:17], v14 offset0:4 offset1:5
	s_or_b32 s10, s0, 8
	s_or_b32 s4, s0, 11
	s_or_b32 s6, s0, 10
	s_or_b32 s8, s0, 9
	s_ashr_i32 s11, s10, 31
	s_ashr_i32 s9, s8, 31
	s_ashr_i32 s7, s6, 31
	s_ashr_i32 s5, s4, 31
	s_lshl_b64 s[10:11], s[10:11], 9
	s_lshl_b64 s[4:5], s[4:5], 9
	s_lshl_b64 s[6:7], s[6:7], 9
	s_lshl_b64 s[8:9], s[8:9], 9
	v_lshl_add_u64 v[6:7], v[4:5], 0, s[10:11]
	v_lshl_add_u64 v[8:9], v[4:5], 0, s[8:9]
	v_lshl_add_u64 v[10:11], v[4:5], 0, s[6:7]
	v_lshl_add_u64 v[12:13], v[4:5], 0, s[4:5]
	s_waitcnt lgkmcnt(0)
	global_store_short v[6:7], v16, off
	global_store_short_d16_hi v[8:9], v16, off
	global_store_short v[10:11], v17, off
	global_store_short_d16_hi v[12:13], v17, off
	ds_read2_b32 v[16:17], v14 offset0:6 offset1:7
	s_or_b32 s10, s0, 12
	s_or_b32 s4, s0, 15
	s_or_b32 s6, s0, 14
	s_or_b32 s8, s0, 13
	s_ashr_i32 s11, s10, 31
	s_ashr_i32 s9, s8, 31
	s_ashr_i32 s7, s6, 31
	s_ashr_i32 s5, s4, 31
	s_lshl_b64 s[10:11], s[10:11], 9
	s_lshl_b64 s[4:5], s[4:5], 9
	s_lshl_b64 s[6:7], s[6:7], 9
	s_lshl_b64 s[8:9], s[8:9], 9
	v_lshl_add_u64 v[6:7], v[4:5], 0, s[10:11]
	v_lshl_add_u64 v[8:9], v[4:5], 0, s[8:9]
	v_lshl_add_u64 v[10:11], v[4:5], 0, s[6:7]
	v_lshl_add_u64 v[12:13], v[4:5], 0, s[4:5]
	s_waitcnt lgkmcnt(0)
; __device__ __forceinline__ void hy_out_tr_item(const Ctx& C, int item) {
;     ...
;     for (int tl = 0; tl < 64; ++tl) yc[(size_t)(tok0 + tl) * 256 + cb * 64 + lane] = tile[lane * 66 + tl];
	global_store_short v[6:7], v16, off
	global_store_short_d16_hi v[8:9], v16, off
	global_store_short v[10:11], v17, off
	global_store_short_d16_hi v[12:13], v17, off
	ds_read2_b32 v[16:17], v14 offset0:8 offset1:9
	s_or_b32 s10, s0, 16
	s_or_b32 s4, s0, 19
	s_or_b32 s6, s0, 18
	s_or_b32 s8, s0, 17
	s_ashr_i32 s11, s10, 31
	s_ashr_i32 s9, s8, 31
	s_ashr_i32 s7, s6, 31
	s_ashr_i32 s5, s4, 31
	s_lshl_b64 s[10:11], s[10:11], 9
	s_lshl_b64 s[4:5], s[4:5], 9
	s_lshl_b64 s[6:7], s[6:7], 9
	s_lshl_b64 s[8:9], s[8:9], 9
	v_lshl_add_u64 v[6:7], v[4:5], 0, s[10:11]
	v_lshl_add_u64 v[8:9], v[4:5], 0, s[8:9]
	v_lshl_add_u64 v[10:11], v[4:5], 0, s[6:7]
	v_lshl_add_u64 v[12:13], v[4:5], 0, s[4:5]
	s_waitcnt lgkmcnt(0)
	global_store_short v[6:7], v16, off
	global_store_short_d16_hi v[8:9], v16, off
	global_store_short v[10:11], v17, off
	global_store_short_d16_hi v[12:13], v17, off
	ds_read2_b32 v[16:17], v14 offset0:10 offset1:11
	s_or_b32 s10, s0, 20
	s_or_b32 s4, s0, 23
	s_or_b32 s6, s0, 22
	s_or_b32 s8, s0, 21
	s_ashr_i32 s11, s10, 31
	s_ashr_i32 s9, s8, 31
	s_ashr_i32 s7, s6, 31
	s_ashr_i32 s5, s4, 31
	s_lshl_b64 s[10:11], s[10:11], 9
	s_lshl_b64 s[4:5], s[4:5], 9
	s_lshl_b64 s[6:7], s[6:7], 9
	s_lshl_b64 s[8:9], s[8:9], 9
	v_lshl_add_u64 v[6:7], v[4:5], 0, s[10:11]
	v_lshl_add_u64 v[8:9], v[4:5], 0, s[8:9]
	v_lshl_add_u64 v[10:11], v[4:5], 0, s[6:7]
	v_lshl_add_u64 v[12:13], v[4:5], 0, s[4:5]
	s_waitcnt lgkmcnt(0)
	global_store_short v[6:7], v16, off
	global_store_short_d16_hi v[8:9], v16, off
	global_store_short v[10:11], v17, off
	global_store_short_d16_hi v[12:13], v17, off
	ds_read2_b32 v[16:17], v14 offset0:12 offset1:13
	s_or_b32 s10, s0, 24
	s_or_b32 s4, s0, 27
	s_or_b32 s6, s0, 26
	s_or_b32 s8, s0, 25
	s_ashr_i32 s11, s10, 31
	s_ashr_i32 s9, s8, 31
	s_ashr_i32 s7, s6, 31
	s_ashr_i32 s5, s4, 31
	s_lshl_b64 s[10:11], s[10:11], 9
	s_lshl_b64 s[4:5], s[4:5], 9
	s_lshl_b64 s[6:7], s[6:7], 9
	s_lshl_b64 s[8:9], s[8:9], 9
	v_lshl_add_u64 v[6:7], v[4:5], 0, s[10:11]
	v_lshl_add_u64 v[8:9], v[4:5], 0, s[8:9]
	v_lshl_add_u64 v[10:11], v[4:5], 0, s[6:7]
	v_lshl_add_u64 v[12:13], v[4:5], 0, s[4:5]
	s_waitcnt lgkmcnt(0)
	global_store_short v[6:7], v16, off
	global_store_short_d16_hi v[8:9], v16, off
	global_store_short v[10:11], v17, off
	global_store_short_d16_hi v[12:13], v17, off
	ds_read2_b32 v[16:17], v14 offset0:14 offset1:15
	s_or_b32 s10, s0, 28
	s_or_b32 s4, s0, 31
	s_or_b32 s6, s0, 30
	s_or_b32 s8, s0, 29
	s_ashr_i32 s11, s10, 31
	s_ashr_i32 s9, s8, 31
	s_ashr_i32 s7, s6, 31
	s_ashr_i32 s5, s4, 31
	s_lshl_b64 s[10:11], s[10:11], 9
	s_lshl_b64 s[4:5], s[4:5], 9
	s_lshl_b64 s[6:7], s[6:7], 9
	s_lshl_b64 s[8:9], s[8:9], 9
	v_lshl_add_u64 v[6:7], v[4:5], 0, s[10:11]
	v_lshl_add_u64 v[8:9], v[4:5], 0, s[8:9]
	v_lshl_add_u64 v[10:11], v[4:5], 0, s[6:7]
	v_lshl_add_u64 v[12:13], v[4:5], 0, s[4:5]
	s_waitcnt lgkmcnt(0)
	global_store_short v[6:7], v16, off
	global_store_short_d16_hi v[8:9], v16, off
	global_store_short v[10:11], v17, off
	global_store_short_d16_hi v[12:13], v17, off
	ds_read2_b32 v[16:17], v14 offset0:16 offset1:17
	s_or_b32 s10, s0, 32
	s_or_b32 s4, s0, 35
	s_or_b32 s6, s0, 34
	s_or_b32 s8, s0, 33
	s_ashr_i32 s11, s10, 31
	s_ashr_i32 s9, s8, 31
	s_ashr_i32 s7, s6, 31
	s_ashr_i32 s5, s4, 31
	s_lshl_b64 s[10:11], s[10:11], 9
	s_lshl_b64 s[4:5], s[4:5], 9
	s_lshl_b64 s[6:7], s[6:7], 9
	s_lshl_b64 s[8:9], s[8:9], 9
	v_lshl_add_u64 v[6:7], v[4:5], 0, s[10:11]
	v_lshl_add_u64 v[8:9], v[4:5], 0, s[8:9]
	v_lshl_add_u64 v[10:11], v[4:5], 0, s[6:7]
	v_lshl_add_u64 v[12:13], v[4:5], 0, s[4:5]
	s_waitcnt lgkmcnt(0)
	global_store_short v[6:7], v16, off
	global_store_short_d16_hi v[8:9], v16, off
	global_store_short v[10:11], v17, off
	global_store_short_d16_hi v[12:13], v17, off
	ds_read2_b32 v[16:17], v14 offset0:18 offset1:19
	s_or_b32 s10, s0, 36
	s_or_b32 s4, s0, 39
	s_or_b32 s6, s0, 38
	s_or_b32 s8, s0, 37
	s_ashr_i32 s11, s10, 31
	s_ashr_i32 s9, s8, 31
	s_ashr_i32 s7, s6, 31
	s_ashr_i32 s5, s4, 31
	s_lshl_b64 s[10:11], s[10:11], 9
	s_lshl_b64 s[4:5], s[4:5], 9
	s_lshl_b64 s[6:7], s[6:7], 9
	s_lshl_b64 s[8:9], s[8:9], 9
	v_lshl_add_u64 v[6:7], v[4:5], 0, s[10:11]
	v_lshl_add_u64 v[8:9], v[4:5], 0, s[8:9]
	v_lshl_add_u64 v[10:11], v[4:5], 0, s[6:7]
	v_lshl_add_u64 v[12:13], v[4:5], 0, s[4:5]
	s_waitcnt lgkmcnt(0)
; __device__ __forceinline__ void hy_out_tr_item(const Ctx& C, int item) {
;     ...
;     for (int tl = 0; tl < 64; ++tl) yc[(size_t)(tok0 + tl) * 256 + cb * 64 + lane] = tile[lane * 66 + tl];
; __global__ void __launch_bounds__(NTHR, 2) fwd_megakernel(Params prm) {
;     ...
;         for (int _m = 0; _m < REP_MIXC; ++_m) { for (int it = bid * 8 + C.wave; it < 2048; it += G * 8) hy_out_tr_item(C, it);
	global_store_short v[6:7], v16, off
	global_store_short_d16_hi v[8:9], v16, off
	global_store_short v[10:11], v17, off
	global_store_short_d16_hi v[12:13], v17, off
	ds_read2_b32 v[16:17], v14 offset0:20 offset1:21
	s_or_b32 s10, s0, 40
	s_or_b32 s4, s0, 43
	s_or_b32 s6, s0, 42
	s_or_b32 s8, s0, 41
	s_ashr_i32 s11, s10, 31
	s_ashr_i32 s9, s8, 31
	s_ashr_i32 s7, s6, 31
	s_ashr_i32 s5, s4, 31
	s_lshl_b64 s[10:11], s[10:11], 9
	s_lshl_b64 s[4:5], s[4:5], 9
	s_lshl_b64 s[6:7], s[6:7], 9
	s_lshl_b64 s[8:9], s[8:9], 9
	v_lshl_add_u64 v[6:7], v[4:5], 0, s[10:11]
	v_lshl_add_u64 v[8:9], v[4:5], 0, s[8:9]
	v_lshl_add_u64 v[10:11], v[4:5], 0, s[6:7]
	v_lshl_add_u64 v[12:13], v[4:5], 0, s[4:5]
	s_waitcnt lgkmcnt(0)
	global_store_short v[6:7], v16, off
	global_store_short_d16_hi v[8:9], v16, off
	global_store_short v[10:11], v17, off
	global_store_short_d16_hi v[12:13], v17, off
	ds_read2_b32 v[16:17], v14 offset0:22 offset1:23
	s_or_b32 s10, s0, 44
	s_or_b32 s4, s0, 47
	s_or_b32 s6, s0, 46
	s_or_b32 s8, s0, 45
	s_ashr_i32 s11, s10, 31
	s_ashr_i32 s9, s8, 31
	s_ashr_i32 s7, s6, 31
	s_ashr_i32 s5, s4, 31
	s_lshl_b64 s[10:11], s[10:11], 9
	s_lshl_b64 s[4:5], s[4:5], 9
	s_lshl_b64 s[6:7], s[6:7], 9
	s_lshl_b64 s[8:9], s[8:9], 9
	v_lshl_add_u64 v[6:7], v[4:5], 0, s[10:11]
	v_lshl_add_u64 v[8:9], v[4:5], 0, s[8:9]
	v_lshl_add_u64 v[10:11], v[4:5], 0, s[6:7]
	v_lshl_add_u64 v[12:13], v[4:5], 0, s[4:5]
	s_waitcnt lgkmcnt(0)
	global_store_short v[6:7], v16, off
	global_store_short_d16_hi v[8:9], v16, off
	global_store_short v[10:11], v17, off
	global_store_short_d16_hi v[12:13], v17, off
	ds_read2_b32 v[16:17], v14 offset0:24 offset1:25
	s_or_b32 s10, s0, 48
	s_or_b32 s4, s0, 51
	s_or_b32 s6, s0, 50
	s_or_b32 s8, s0, 49
	s_ashr_i32 s11, s10, 31
	s_ashr_i32 s9, s8, 31
	s_ashr_i32 s7, s6, 31
	s_ashr_i32 s5, s4, 31
	s_lshl_b64 s[10:11], s[10:11], 9
	s_lshl_b64 s[4:5], s[4:5], 9
	s_lshl_b64 s[6:7], s[6:7], 9
	s_lshl_b64 s[8:9], s[8:9], 9
	v_lshl_add_u64 v[6:7], v[4:5], 0, s[10:11]
	v_lshl_add_u64 v[8:9], v[4:5], 0, s[8:9]
	v_lshl_add_u64 v[10:11], v[4:5], 0, s[6:7]
	v_lshl_add_u64 v[12:13], v[4:5], 0, s[4:5]
	s_waitcnt lgkmcnt(0)
	global_store_short v[6:7], v16, off
	global_store_short_d16_hi v[8:9], v16, off
	global_store_short v[10:11], v17, off
	global_store_short_d16_hi v[12:13], v17, off
	ds_read2_b32 v[16:17], v14 offset0:26 offset1:27
	s_or_b32 s10, s0, 52
	s_or_b32 s4, s0, 55
	s_or_b32 s6, s0, 54
	s_or_b32 s8, s0, 53
	s_ashr_i32 s11, s10, 31
	s_ashr_i32 s9, s8, 31
	s_ashr_i32 s7, s6, 31
	s_ashr_i32 s5, s4, 31
	s_lshl_b64 s[10:11], s[10:11], 9
	s_lshl_b64 s[4:5], s[4:5], 9
	s_lshl_b64 s[6:7], s[6:7], 9
	s_lshl_b64 s[8:9], s[8:9], 9
	v_lshl_add_u64 v[6:7], v[4:5], 0, s[10:11]
	v_lshl_add_u64 v[8:9], v[4:5], 0, s[8:9]
	v_lshl_add_u64 v[10:11], v[4:5], 0, s[6:7]
	v_lshl_add_u64 v[12:13], v[4:5], 0, s[4:5]
	s_waitcnt lgkmcnt(0)
	global_store_short v[6:7], v16, off
	global_store_short_d16_hi v[8:9], v16, off
	global_store_short v[10:11], v17, off
	global_store_short_d16_hi v[12:13], v17, off
	ds_read2_b32 v[16:17], v14 offset0:28 offset1:29
	s_or_b32 s10, s0, 56
	s_or_b32 s4, s0, 59
	s_or_b32 s6, s0, 58
	s_or_b32 s8, s0, 57
	s_ashr_i32 s11, s10, 31
	s_ashr_i32 s9, s8, 31
	s_ashr_i32 s7, s6, 31
	s_ashr_i32 s5, s4, 31
	s_lshl_b64 s[10:11], s[10:11], 9
	s_lshl_b64 s[4:5], s[4:5], 9
	s_lshl_b64 s[6:7], s[6:7], 9
	s_lshl_b64 s[8:9], s[8:9], 9
	v_lshl_add_u64 v[6:7], v[4:5], 0, s[10:11]
	v_lshl_add_u64 v[8:9], v[4:5], 0, s[8:9]
	v_lshl_add_u64 v[10:11], v[4:5], 0, s[6:7]
	v_lshl_add_u64 v[12:13], v[4:5], 0, s[4:5]
	s_waitcnt lgkmcnt(0)
	global_store_short v[6:7], v16, off
	global_store_short_d16_hi v[8:9], v16, off
	global_store_short v[10:11], v17, off
	global_store_short_d16_hi v[12:13], v17, off
	ds_read2_b32 v[12:13], v14 offset0:30 offset1:31
	s_or_b32 s4, s0, 63
	s_or_b32 s6, s0, 62
	s_or_b32 s8, s0, 61
	s_or_b32 s0, s0, 60
	s_ashr_i32 s1, s0, 31
	s_ashr_i32 s9, s8, 31
	s_ashr_i32 s7, s6, 31
	s_ashr_i32 s5, s4, 31
	s_lshl_b64 s[0:1], s[0:1], 9
	s_lshl_b64 s[4:5], s[4:5], 9
	s_lshl_b64 s[6:7], s[6:7], 9
	s_lshl_b64 s[8:9], s[8:9], 9
	v_lshl_add_u64 v[6:7], v[4:5], 0, s[0:1]
	v_lshl_add_u64 v[8:9], v[4:5], 0, s[8:9]
	v_lshl_add_u64 v[10:11], v[4:5], 0, s[6:7]
	v_lshl_add_u64 v[4:5], v[4:5], 0, s[4:5]
	s_waitcnt lgkmcnt(0)
	global_store_short v[6:7], v12, off
	global_store_short_d16_hi v[8:9], v12, off
	global_store_short v[10:11], v13, off
	global_store_short_d16_hi v[4:5], v13, off
	s_waitcnt lgkmcnt(0)
	v_readlane_b32 s0, v254, 20
	s_cmpk_eq_i32 s26, 0x100
	s_cselect_b32 s0, 0x400, s0
	s_add_i32 s68, s68, s0
	s_cmpk_gt_i32 s68, 0x7ff
	v_readlane_b32 s1, v254, 21
	s_cbranch_scc0 .LBB0_748
